# merge gates clamped to >=1/255 where produced; per-use v_max dropped in the branch-GEMM epilogue (248 VALU per unit)
# speedup vs baseline: 1.0122x; 1.0009x over previous
; __device__ __forceinline__ unsigned cvtpk(float lo, float hi) { unsigned r; asm volatile("v_cvt_pk_bf16_f32 %0, %1, %2" : "=v"(r) : "v"(lo), "v"(hi)); return r; }
;     __device__ __forceinline__ void operator()(f32x4 (&acc)[2][2][4][2], const pg8::Unit& u, int wr, int wc, int fr, int fq) const {
;     ...
;             for (int m = 0; m < 4; ++m) {
;                 u16* op = hbuf + (size_t)(row0 + ai * 128 + m * 16) * DM + (u.pn & 3) * 256 + cin;
; #pragma unroll
;                 for (int bj = 0; bj < 2; ++bj) {
;                     f32x4 vv[2];
; #pragma unroll
;                     for (int n = 0; n < 2; ++n) {
;                         const unsigned a4 = ga[m][bj][n], b4 = gb[m][bj][n]; f32x4 v = acc[ai][bj][m][n];
; #pragma unroll
;                         for (int j = 0; j < 4; ++j) { const float ga_ = fmaxf((float)((a4 >> (8 * j)) & 255u), 1.f), gb_ = fmaxf((float)((b4 >> (8 * j)) & 255u), 1.f);
;                             v[j] *= last ? ga_ * (1.f / 255.f) : ga_ * __builtin_amdgcn_rcpf(gb_); }
;                         vv[n] = v; if (!last) acc[ai][bj][m][n] = v;
;                     }
;                     if (last) { u32x4 o = {cvtpk(vv[0][0], vv[0][1]), cvtpk(vv[0][2], vv[0][3]), cvtpk(vv[1][0], vv[1][1]), cvtpk(vv[1][2], vv[1][3])}; *(u32x4*)(op + bj * 128) = o; }
.LBB0_40:
	v_lshlrev_b64 v[194:195], 11, v[144:145]
	s_waitcnt vmcnt(0)
	v_cvt_f32_ubyte0_e32 v145, v196
	v_rcp_f32_e32 v145, v145
	v_cvt_f32_ubyte0_e32 v213, v192
	v_cvt_f32_ubyte1_e32 v216, v193
	v_cndmask_b32_e64 v145, v145, v203, s[38:39]
	v_mul_f32_e32 v145, v213, v145
	v_cvt_f32_ubyte1_e32 v213, v196
	v_rcp_f32_e32 v214, v213
	v_mul_f32_e32 v213, v126, v145
	v_cvt_f32_ubyte1_e32 v145, v192
	v_cndmask_b32_e64 v214, v214, v203, s[38:39]
	v_mul_f32_e32 v145, v145, v214
	v_cvt_f32_ubyte2_e32 v214, v196
	v_rcp_f32_e32 v215, v214
	v_mul_f32_e32 v214, v127, v145
	v_cvt_f32_ubyte2_e32 v145, v192
	v_cvt_f32_ubyte3_e32 v196, v196
	v_cndmask_b32_e64 v215, v215, v203, s[38:39]
	v_mul_f32_e32 v145, v145, v215
	v_rcp_f32_e32 v215, v196
	v_mul_f32_e32 v196, v128, v145
	v_cvt_f32_ubyte3_e32 v145, v192
	v_cndmask_b32_e64 v192, v215, v203, s[38:39]
	v_mul_f32_e32 v145, v145, v192
	v_cvt_f32_ubyte0_e32 v192, v197
	v_rcp_f32_e32 v192, v192
	v_mul_f32_e32 v215, v129, v145
	v_cvt_f32_ubyte0_e32 v145, v193
	v_cndmask_b32_e64 v192, v192, v203, s[38:39]
	v_mul_f32_e32 v145, v145, v192
	v_cvt_f32_ubyte1_e32 v192, v197
	v_rcp_f32_e32 v192, v192
	v_cvt_f32_ubyte2_e32 v217, v193
	v_cndmask_b32_e64 v192, v192, v203, s[38:39]
	v_mul_f32_e32 v192, v216, v192
	v_cvt_f32_ubyte2_e32 v216, v197
	v_rcp_f32_e32 v216, v216
	v_cvt_f32_ubyte3_e32 v197, v197
	s_and_b32 s1, s30, 0x300
	v_cndmask_b32_e64 v216, v216, v203, s[38:39]
	v_mul_f32_e32 v216, v217, v216
	v_rcp_f32_e32 v217, v197
	v_cvt_f32_ubyte3_e32 v193, v193
	v_lshl_add_u64 v[194:195], s[12:13], 0, v[194:195]
	s_lshl_b32 s30, s1, 1
	v_mul_f32_e32 v197, v124, v216
	v_cndmask_b32_e64 v216, v217, v203, s[38:39]
	v_lshl_add_u64 v[194:195], v[194:195], 0, s[30:31]
	v_mul_f32_e32 v193, v193, v216
	v_cndmask_b32_e64 v216, 0, 1, s[38:39]
	v_lshl_add_u64 v[194:195], v[194:195], 0, v[0:1]
	v_mul_f32_e32 v145, v122, v145
	v_mul_f32_e32 v192, v123, v192
	v_cmp_ne_u32_e64 s[40:41], 1, v216
	s_andn2_b64 vcc, exec, s[38:39]
	v_mul_f32_e32 v193, v125, v193
	s_cbranch_vccnz .LBB0_42
	v_cvt_pk_bf16_f32 v216, v213, v214
	v_cvt_pk_bf16_f32 v217, v196, v215
	v_cvt_pk_bf16_f32 v218, v145, v192
	v_cvt_pk_bf16_f32 v219, v197, v193
	global_store_dwordx4 v[194:195], v[216:219], off
	s_branch .LBB0_43

; __device__ __forceinline__ unsigned cvtpk(float lo, float hi) { unsigned r; asm volatile("v_cvt_pk_bf16_f32 %0, %1, %2" : "=v"(r) : "v"(lo), "v"(hi)); return r; }
;     __device__ __forceinline__ void operator()(f32x4 (&acc)[2][2][4][2], const pg8::Unit& u, int wr, int wc, int fr, int fq) const {
;     ...
;                 for (int bj = 0; bj < 2; ++bj) {
;                     f32x4 vv[2];
; #pragma unroll
;                     for (int n = 0; n < 2; ++n) {
;                         const unsigned a4 = ga[m][bj][n], b4 = gb[m][bj][n]; f32x4 v = acc[ai][bj][m][n];
; #pragma unroll
;                         for (int j = 0; j < 4; ++j) { const float ga_ = fmaxf((float)((a4 >> (8 * j)) & 255u), 1.f), gb_ = fmaxf((float)((b4 >> (8 * j)) & 255u), 1.f);
;                             v[j] *= last ? ga_ * (1.f / 255.f) : ga_ * __builtin_amdgcn_rcpf(gb_); }
;                         vv[n] = v; if (!last) acc[ai][bj][m][n] = v;
;                     }
;                     if (last) { u32x4 o = {cvtpk(vv[0][0], vv[0][1]), cvtpk(vv[0][2], vv[0][3]), cvtpk(vv[1][0], vv[1][1]), cvtpk(vv[1][2], vv[1][3])}; *(u32x4*)(op + bj * 128) = o; }
.LBB0_43:
	v_cvt_f32_ubyte0_e32 v145, v188
	v_rcp_f32_e32 v145, v145
	v_cvt_f32_ubyte0_e32 v192, v190
	v_cvt_f32_ubyte1_e32 v193, v188
	v_cndmask_b32_e64 v145, v145, v203, s[38:39]
	v_mul_f32_e32 v145, v192, v145
	v_max_f32_e32 v192, 1.0, v193
	v_rcp_f32_e32 v192, v192
	v_mul_f32_e32 v197, v94, v145
	v_cvt_f32_ubyte1_e32 v145, v190
	v_cndmask_b32_e64 v192, v192, v203, s[38:39]
	v_mul_f32_e32 v145, v145, v192
	v_cvt_f32_ubyte2_e32 v192, v188
	v_rcp_f32_e32 v192, v192
	v_cvt_f32_ubyte3_e32 v188, v188
	v_mul_f32_e32 v216, v95, v145
	v_cvt_f32_ubyte2_e32 v145, v190
	v_rcp_f32_e32 v188, v188
	v_cndmask_b32_e64 v192, v192, v203, s[38:39]
	v_mul_f32_e32 v145, v145, v192
	v_mul_f32_e32 v217, v96, v145
	v_cvt_f32_ubyte3_e32 v145, v190
	v_cndmask_b32_e64 v188, v188, v203, s[38:39]
	v_mul_f32_e32 v145, v145, v188
	v_cvt_f32_ubyte0_e32 v188, v189
	v_rcp_f32_e32 v188, v188
	v_mul_f32_e32 v218, v97, v145
	v_cvt_f32_ubyte0_e32 v145, v191
	v_cndmask_b32_e64 v188, v188, v203, s[38:39]
	v_mul_f32_e32 v145, v145, v188
	v_cvt_f32_ubyte1_e32 v188, v189
	v_rcp_f32_e32 v188, v188
	v_cvt_f32_ubyte1_e32 v190, v191
	v_cvt_f32_ubyte2_e32 v192, v191
	v_cndmask_b32_e64 v188, v188, v203, s[38:39]
	v_mul_f32_e32 v188, v190, v188
	v_cvt_f32_ubyte2_e32 v190, v189
	v_rcp_f32_e32 v190, v190
	v_cvt_f32_ubyte3_e32 v189, v189
	v_cndmask_b32_e64 v190, v190, v203, s[38:39]
	v_mul_f32_e32 v190, v192, v190
	v_rcp_f32_e32 v192, v189
	v_mul_f32_e32 v189, v92, v190
	v_cvt_f32_ubyte3_e32 v190, v191
	v_cndmask_b32_e64 v191, v192, v203, s[38:39]
	v_mul_f32_e32 v190, v190, v191
	v_mul_f32_e32 v145, v90, v145
	v_mul_f32_e32 v188, v91, v188
	s_and_b64 vcc, exec, s[40:41]
	v_mul_f32_e32 v190, v93, v190
	s_cbranch_vccnz .LBB0_45
	v_cvt_pk_bf16_f32 v220, v197, v216
	v_cvt_pk_bf16_f32 v221, v217, v218
	v_cvt_pk_bf16_f32 v222, v145, v188
	v_cvt_pk_bf16_f32 v223, v189, v190
	global_store_dwordx4 v[194:195], v[220:223], off offset:256
	s_branch .LBB0_46

; __device__ __forceinline__ unsigned cvtpk(float lo, float hi) { unsigned r; asm volatile("v_cvt_pk_bf16_f32 %0, %1, %2" : "=v"(r) : "v"(lo), "v"(hi)); return r; }
;     __device__ __forceinline__ void operator()(f32x4 (&acc)[2][2][4][2], const pg8::Unit& u, int wr, int wc, int fr, int fq) const {
;     ...
;                 for (int bj = 0; bj < 2; ++bj) {
;                     f32x4 vv[2];
; #pragma unroll
;                     for (int n = 0; n < 2; ++n) {
;                         const unsigned a4 = ga[m][bj][n], b4 = gb[m][bj][n]; f32x4 v = acc[ai][bj][m][n];
; #pragma unroll
;                         for (int j = 0; j < 4; ++j) { const float ga_ = fmaxf((float)((a4 >> (8 * j)) & 255u), 1.f), gb_ = fmaxf((float)((b4 >> (8 * j)) & 255u), 1.f);
;                             v[j] *= last ? ga_ * (1.f / 255.f) : ga_ * __builtin_amdgcn_rcpf(gb_); }
;                         vv[n] = v; if (!last) acc[ai][bj][m][n] = v;
;                     }
;                     if (last) { u32x4 o = {cvtpk(vv[0][0], vv[0][1]), cvtpk(vv[0][2], vv[0][3]), cvtpk(vv[1][0], vv[1][1]), cvtpk(vv[1][2], vv[1][3])}; *(u32x4*)(op + bj * 128) = o; }
.LBB0_46:
	v_cvt_f32_ubyte0_e32 v145, v184
	v_rcp_f32_e32 v145, v145
	v_cvt_f32_ubyte0_e32 v188, v182
	v_lshlrev_b64 v[186:187], 11, v[186:187]
	v_cndmask_b32_e64 v145, v145, v203, s[38:39]
	v_mul_f32_e32 v145, v188, v145
	v_cvt_f32_ubyte1_e32 v188, v184
	v_rcp_f32_e32 v188, v188
	v_mul_f32_e32 v219, v118, v145
	v_cvt_f32_ubyte1_e32 v145, v182
	v_cndmask_b32_e64 v188, v188, v203, s[38:39]
	v_mul_f32_e32 v145, v145, v188
	v_cvt_f32_ubyte2_e32 v188, v184
	v_rcp_f32_e32 v188, v188
	v_cvt_f32_ubyte3_e32 v184, v184
	v_mul_f32_e32 v220, v119, v145
	v_cvt_f32_ubyte2_e32 v145, v182
	v_rcp_f32_e32 v184, v184
	v_cndmask_b32_e64 v188, v188, v203, s[38:39]
	v_mul_f32_e32 v145, v145, v188
	v_mul_f32_e32 v221, v120, v145
	v_cvt_f32_ubyte3_e32 v145, v182
	v_cndmask_b32_e64 v182, v184, v203, s[38:39]
	v_mul_f32_e32 v145, v145, v182
	v_cvt_f32_ubyte0_e32 v182, v185
	v_rcp_f32_e32 v182, v182
	v_mul_f32_e32 v222, v121, v145
	v_cvt_f32_ubyte0_e32 v145, v183
	v_cndmask_b32_e64 v182, v182, v203, s[38:39]
	v_mul_f32_e32 v145, v145, v182
	v_cvt_f32_ubyte1_e32 v182, v185
	v_rcp_f32_e32 v182, v182
	v_cvt_f32_ubyte1_e32 v184, v183
	v_cvt_f32_ubyte2_e32 v188, v183
	v_cndmask_b32_e64 v182, v182, v203, s[38:39]
	v_mul_f32_e32 v182, v184, v182
	v_cvt_f32_ubyte2_e32 v184, v185
	v_cvt_f32_ubyte3_e32 v185, v185
	v_rcp_f32_e32 v184, v184
	v_rcp_f32_e32 v185, v185
	v_cvt_f32_ubyte3_e32 v183, v183
	v_lshl_add_u64 v[186:187], s[12:13], 0, v[186:187]
	v_cndmask_b32_e64 v184, v184, v203, s[38:39]
	v_cndmask_b32_e64 v185, v185, v203, s[38:39]
	v_lshl_add_u64 v[186:187], v[186:187], 0, s[30:31]
	v_mul_f32_e32 v184, v188, v184
	v_mul_f32_e32 v183, v183, v185
	v_lshl_add_u64 v[186:187], v[186:187], 0, v[0:1]
	v_mul_f32_e32 v145, v114, v145
	v_mul_f32_e32 v182, v115, v182
	v_mul_f32_e32 v184, v116, v184
	s_and_b64 vcc, exec, s[40:41]
	v_mul_f32_e32 v183, v117, v183
	s_cbranch_vccnz .LBB0_48
	v_cvt_pk_bf16_f32 v188, v219, v220
	v_cvt_pk_bf16_f32 v189, v221, v222
	v_cvt_pk_bf16_f32 v190, v145, v182
	v_cvt_pk_bf16_f32 v191, v184, v183
	global_store_dwordx4 v[186:187], v[188:191], off
	s_branch .LBB0_49

; __device__ __forceinline__ unsigned cvtpk(float lo, float hi) { unsigned r; asm volatile("v_cvt_pk_bf16_f32 %0, %1, %2" : "=v"(r) : "v"(lo), "v"(hi)); return r; }
;     __device__ __forceinline__ void operator()(f32x4 (&acc)[2][2][4][2], const pg8::Unit& u, int wr, int wc, int fr, int fq) const {
;     ...
;                 for (int bj = 0; bj < 2; ++bj) {
;                     f32x4 vv[2];
; #pragma unroll
;                     for (int n = 0; n < 2; ++n) {
;                         const unsigned a4 = ga[m][bj][n], b4 = gb[m][bj][n]; f32x4 v = acc[ai][bj][m][n];
; #pragma unroll
;                         for (int j = 0; j < 4; ++j) { const float ga_ = fmaxf((float)((a4 >> (8 * j)) & 255u), 1.f), gb_ = fmaxf((float)((b4 >> (8 * j)) & 255u), 1.f);
;                             v[j] *= last ? ga_ * (1.f / 255.f) : ga_ * __builtin_amdgcn_rcpf(gb_); }
;                         vv[n] = v; if (!last) acc[ai][bj][m][n] = v;
;                     }
;                     if (last) { u32x4 o = {cvtpk(vv[0][0], vv[0][1]), cvtpk(vv[0][2], vv[0][3]), cvtpk(vv[1][0], vv[1][1]), cvtpk(vv[1][2], vv[1][3])}; *(u32x4*)(op + bj * 128) = o; }
.LBB0_49:
	v_cvt_f32_ubyte0_e32 v145, v178
	v_rcp_f32_e32 v145, v145
	v_cvt_f32_ubyte0_e32 v182, v180
	v_cvt_f32_ubyte1_e32 v183, v178
	v_cndmask_b32_e64 v145, v145, v203, s[38:39]
	v_mul_f32_e32 v145, v182, v145
	v_max_f32_e32 v182, 1.0, v183
	v_rcp_f32_e32 v182, v182
	v_mul_f32_e32 v223, v86, v145
	v_cvt_f32_ubyte1_e32 v145, v180
	v_cndmask_b32_e64 v182, v182, v203, s[38:39]
	v_mul_f32_e32 v145, v145, v182
	v_cvt_f32_ubyte2_e32 v182, v178
	v_rcp_f32_e32 v182, v182
	v_cvt_f32_ubyte3_e32 v178, v178
	v_mul_f32_e32 v224, v87, v145
	v_cvt_f32_ubyte2_e32 v145, v180
	v_rcp_f32_e32 v178, v178
	v_cndmask_b32_e64 v182, v182, v203, s[38:39]
	v_mul_f32_e32 v145, v145, v182
	v_mul_f32_e32 v225, v88, v145
	v_cvt_f32_ubyte3_e32 v145, v180
	v_cndmask_b32_e64 v178, v178, v203, s[38:39]
	v_mul_f32_e32 v145, v145, v178
	v_cvt_f32_ubyte0_e32 v178, v179
	v_rcp_f32_e32 v178, v178
	v_mul_f32_e32 v226, v89, v145
	v_cvt_f32_ubyte0_e32 v145, v181
	v_cndmask_b32_e64 v178, v178, v203, s[38:39]
	v_mul_f32_e32 v145, v145, v178
	v_cvt_f32_ubyte1_e32 v178, v179
	v_rcp_f32_e32 v178, v178
	v_cvt_f32_ubyte1_e32 v180, v181
	v_cvt_f32_ubyte2_e32 v182, v181
	v_cndmask_b32_e64 v178, v178, v203, s[38:39]
	v_mul_f32_e32 v178, v180, v178
	v_cvt_f32_ubyte2_e32 v180, v179
	v_rcp_f32_e32 v180, v180
	v_cvt_f32_ubyte3_e32 v179, v179
	v_cndmask_b32_e64 v180, v180, v203, s[38:39]
	v_mul_f32_e32 v180, v182, v180
	v_rcp_f32_e32 v182, v179
	v_mul_f32_e32 v179, v84, v180
	v_cvt_f32_ubyte3_e32 v180, v181
	v_cndmask_b32_e64 v181, v182, v203, s[38:39]
	v_mul_f32_e32 v180, v180, v181
	v_mul_f32_e32 v145, v82, v145
	v_mul_f32_e32 v178, v83, v178
	s_and_b64 vcc, exec, s[40:41]
	v_mul_f32_e32 v180, v85, v180
	s_cbranch_vccnz .LBB0_51
	v_cvt_pk_bf16_f32 v182, v223, v224
	v_cvt_pk_bf16_f32 v183, v225, v226
	v_cvt_pk_bf16_f32 v184, v145, v178
	v_cvt_pk_bf16_f32 v185, v179, v180
	global_store_dwordx4 v[186:187], v[182:185], off offset:256
	s_branch .LBB0_52

; __device__ __forceinline__ unsigned cvtpk(float lo, float hi) { unsigned r; asm volatile("v_cvt_pk_bf16_f32 %0, %1, %2" : "=v"(r) : "v"(lo), "v"(hi)); return r; }
;     __device__ __forceinline__ void operator()(f32x4 (&acc)[2][2][4][2], const pg8::Unit& u, int wr, int wc, int fr, int fq) const {
;     ...
;                 for (int bj = 0; bj < 2; ++bj) {
;                     f32x4 vv[2];
; #pragma unroll
;                     for (int n = 0; n < 2; ++n) {
;                         const unsigned a4 = ga[m][bj][n], b4 = gb[m][bj][n]; f32x4 v = acc[ai][bj][m][n];
; #pragma unroll
;                         for (int j = 0; j < 4; ++j) { const float ga_ = fmaxf((float)((a4 >> (8 * j)) & 255u), 1.f), gb_ = fmaxf((float)((b4 >> (8 * j)) & 255u), 1.f);
;                             v[j] *= last ? ga_ * (1.f / 255.f) : ga_ * __builtin_amdgcn_rcpf(gb_); }
;                         vv[n] = v; if (!last) acc[ai][bj][m][n] = v;
;                     }
;                     if (last) { u32x4 o = {cvtpk(vv[0][0], vv[0][1]), cvtpk(vv[0][2], vv[0][3]), cvtpk(vv[1][0], vv[1][1]), cvtpk(vv[1][2], vv[1][3])}; *(u32x4*)(op + bj * 128) = o; }
.LBB0_52:
	v_cvt_f32_ubyte0_e32 v145, v174
	v_rcp_f32_e32 v145, v145
	v_cvt_f32_ubyte0_e32 v178, v172
	v_lshlrev_b64 v[176:177], 11, v[176:177]
	v_cndmask_b32_e64 v145, v145, v203, s[38:39]
	v_mul_f32_e32 v145, v178, v145
	v_cvt_f32_ubyte1_e32 v178, v174
	v_rcp_f32_e32 v178, v178
	v_mul_f32_e32 v227, v110, v145
	v_cvt_f32_ubyte1_e32 v145, v172
	v_cndmask_b32_e64 v178, v178, v203, s[38:39]
	v_mul_f32_e32 v145, v145, v178
	v_cvt_f32_ubyte2_e32 v178, v174
	v_rcp_f32_e32 v178, v178
	v_cvt_f32_ubyte3_e32 v174, v174
	v_mul_f32_e32 v228, v111, v145
	v_cvt_f32_ubyte2_e32 v145, v172
	v_rcp_f32_e32 v174, v174
	v_cndmask_b32_e64 v178, v178, v203, s[38:39]
	v_mul_f32_e32 v145, v145, v178
	v_mul_f32_e32 v229, v112, v145
	v_cvt_f32_ubyte3_e32 v145, v172
	v_cndmask_b32_e64 v172, v174, v203, s[38:39]
	v_mul_f32_e32 v145, v145, v172
	v_cvt_f32_ubyte0_e32 v172, v175
	v_rcp_f32_e32 v172, v172
	v_mul_f32_e32 v230, v113, v145
	v_cvt_f32_ubyte0_e32 v145, v173
	v_cndmask_b32_e64 v172, v172, v203, s[38:39]
	v_mul_f32_e32 v145, v145, v172
	v_cvt_f32_ubyte1_e32 v172, v175
	v_rcp_f32_e32 v172, v172
	v_cvt_f32_ubyte1_e32 v174, v173
	v_cvt_f32_ubyte2_e32 v178, v173
	v_cndmask_b32_e64 v172, v172, v203, s[38:39]
	v_mul_f32_e32 v172, v174, v172
	v_cvt_f32_ubyte2_e32 v174, v175
	v_cvt_f32_ubyte3_e32 v175, v175
	v_rcp_f32_e32 v174, v174
	v_rcp_f32_e32 v175, v175
	v_cvt_f32_ubyte3_e32 v173, v173
	v_lshl_add_u64 v[176:177], s[12:13], 0, v[176:177]
	v_cndmask_b32_e64 v174, v174, v203, s[38:39]
	v_cndmask_b32_e64 v175, v175, v203, s[38:39]
	v_lshl_add_u64 v[176:177], v[176:177], 0, s[30:31]
	v_mul_f32_e32 v174, v178, v174
	v_mul_f32_e32 v173, v173, v175
	v_lshl_add_u64 v[176:177], v[176:177], 0, v[0:1]
	v_mul_f32_e32 v145, v106, v145
	v_mul_f32_e32 v172, v107, v172
	v_mul_f32_e32 v174, v108, v174
	s_and_b64 vcc, exec, s[40:41]
	v_mul_f32_e32 v173, v109, v173
	s_cbranch_vccnz .LBB0_54
	v_cvt_pk_bf16_f32 v178, v227, v228
	v_cvt_pk_bf16_f32 v179, v229, v230
	v_cvt_pk_bf16_f32 v180, v145, v172
	v_cvt_pk_bf16_f32 v181, v174, v173
	global_store_dwordx4 v[176:177], v[178:181], off
	s_branch .LBB0_55

; __device__ __forceinline__ unsigned cvtpk(float lo, float hi) { unsigned r; asm volatile("v_cvt_pk_bf16_f32 %0, %1, %2" : "=v"(r) : "v"(lo), "v"(hi)); return r; }
;     __device__ __forceinline__ void operator()(f32x4 (&acc)[2][2][4][2], const pg8::Unit& u, int wr, int wc, int fr, int fq) const {
;     ...
;                 for (int bj = 0; bj < 2; ++bj) {
;                     f32x4 vv[2];
; #pragma unroll
;                     for (int n = 0; n < 2; ++n) {
;                         const unsigned a4 = ga[m][bj][n], b4 = gb[m][bj][n]; f32x4 v = acc[ai][bj][m][n];
; #pragma unroll
;                         for (int j = 0; j < 4; ++j) { const float ga_ = fmaxf((float)((a4 >> (8 * j)) & 255u), 1.f), gb_ = fmaxf((float)((b4 >> (8 * j)) & 255u), 1.f);
;                             v[j] *= last ? ga_ * (1.f / 255.f) : ga_ * __builtin_amdgcn_rcpf(gb_); }
;                         vv[n] = v; if (!last) acc[ai][bj][m][n] = v;
;                     }
;                     if (last) { u32x4 o = {cvtpk(vv[0][0], vv[0][1]), cvtpk(vv[0][2], vv[0][3]), cvtpk(vv[1][0], vv[1][1]), cvtpk(vv[1][2], vv[1][3])}; *(u32x4*)(op + bj * 128) = o; }
.LBB0_55:
	v_cvt_f32_ubyte0_e32 v145, v158
	v_rcp_f32_e32 v145, v145
	v_cvt_f32_ubyte0_e32 v172, v160
	v_cvt_f32_ubyte1_e32 v173, v158
	v_cndmask_b32_e64 v145, v145, v203, s[38:39]
	v_mul_f32_e32 v145, v172, v145
	v_max_f32_e32 v172, 1.0, v173
	v_rcp_f32_e32 v172, v172
	v_mul_f32_e32 v231, v78, v145
	v_cvt_f32_ubyte1_e32 v145, v160
	v_cndmask_b32_e64 v172, v172, v203, s[38:39]
	v_mul_f32_e32 v145, v145, v172
	v_cvt_f32_ubyte2_e32 v172, v158
	v_rcp_f32_e32 v172, v172
	v_cvt_f32_ubyte3_e32 v158, v158
	v_mul_f32_e32 v232, v79, v145
	v_cvt_f32_ubyte2_e32 v145, v160
	v_rcp_f32_e32 v158, v158
	v_cndmask_b32_e64 v172, v172, v203, s[38:39]
	v_mul_f32_e32 v145, v145, v172
	v_mul_f32_e32 v233, v80, v145
	v_cvt_f32_ubyte3_e32 v145, v160
	v_cndmask_b32_e64 v158, v158, v203, s[38:39]
	v_mul_f32_e32 v145, v145, v158
	v_cvt_f32_ubyte0_e32 v158, v159
	v_rcp_f32_e32 v158, v158
	v_mul_f32_e32 v234, v81, v145
	v_cvt_f32_ubyte0_e32 v145, v161
	v_cndmask_b32_e64 v158, v158, v203, s[38:39]
	v_mul_f32_e32 v145, v145, v158
	v_cvt_f32_ubyte1_e32 v158, v159
	v_rcp_f32_e32 v158, v158
	v_cvt_f32_ubyte1_e32 v160, v161
	v_cvt_f32_ubyte2_e32 v172, v161
	v_cndmask_b32_e64 v158, v158, v203, s[38:39]
	v_mul_f32_e32 v158, v160, v158
	v_cvt_f32_ubyte2_e32 v160, v159
	v_rcp_f32_e32 v160, v160
	v_cvt_f32_ubyte3_e32 v159, v159
	v_cndmask_b32_e64 v160, v160, v203, s[38:39]
	v_mul_f32_e32 v160, v172, v160
	v_rcp_f32_e32 v172, v159
	v_mul_f32_e32 v159, v76, v160
	v_cvt_f32_ubyte3_e32 v160, v161
	v_cndmask_b32_e64 v161, v172, v203, s[38:39]
	v_mul_f32_e32 v160, v160, v161
	v_mul_f32_e32 v145, v74, v145
	v_mul_f32_e32 v158, v75, v158
	s_and_b64 vcc, exec, s[40:41]
	v_mul_f32_e32 v160, v77, v160
	s_cbranch_vccnz .LBB0_57
	v_cvt_pk_bf16_f32 v172, v231, v232
	v_cvt_pk_bf16_f32 v173, v233, v234
	v_cvt_pk_bf16_f32 v174, v145, v158
	v_cvt_pk_bf16_f32 v175, v159, v160
	global_store_dwordx4 v[176:177], v[172:175], off offset:256
	s_branch .LBB0_58

; __device__ __forceinline__ unsigned cvtpk(float lo, float hi) { unsigned r; asm volatile("v_cvt_pk_bf16_f32 %0, %1, %2" : "=v"(r) : "v"(lo), "v"(hi)); return r; }
;     __device__ __forceinline__ void operator()(f32x4 (&acc)[2][2][4][2], const pg8::Unit& u, int wr, int wc, int fr, int fq) const {
;     ...
;                 for (int bj = 0; bj < 2; ++bj) {
;                     f32x4 vv[2];
; #pragma unroll
;                     for (int n = 0; n < 2; ++n) {
;                         const unsigned a4 = ga[m][bj][n], b4 = gb[m][bj][n]; f32x4 v = acc[ai][bj][m][n];
; #pragma unroll
;                         for (int j = 0; j < 4; ++j) { const float ga_ = fmaxf((float)((a4 >> (8 * j)) & 255u), 1.f), gb_ = fmaxf((float)((b4 >> (8 * j)) & 255u), 1.f);
;                             v[j] *= last ? ga_ * (1.f / 255.f) : ga_ * __builtin_amdgcn_rcpf(gb_); }
;                         vv[n] = v; if (!last) acc[ai][bj][m][n] = v;
;                     }
;                     if (last) { u32x4 o = {cvtpk(vv[0][0], vv[0][1]), cvtpk(vv[0][2], vv[0][3]), cvtpk(vv[1][0], vv[1][1]), cvtpk(vv[1][2], vv[1][3])}; *(u32x4*)(op + bj * 128) = o; }
.LBB0_58:
	v_cvt_f32_ubyte0_e32 v145, v154
	v_rcp_f32_e32 v145, v145
	v_cvt_f32_ubyte0_e32 v158, v152
	v_lshlrev_b64 v[156:157], 11, v[156:157]
	v_cndmask_b32_e64 v145, v145, v203, s[38:39]
	v_mul_f32_e32 v145, v158, v145
	v_cvt_f32_ubyte1_e32 v158, v154
	v_rcp_f32_e32 v158, v158
	v_mul_f32_e32 v235, v102, v145
	v_cvt_f32_ubyte1_e32 v145, v152
	v_cndmask_b32_e64 v158, v158, v203, s[38:39]
	v_mul_f32_e32 v145, v145, v158
	v_cvt_f32_ubyte2_e32 v158, v154
	v_rcp_f32_e32 v158, v158
	v_cvt_f32_ubyte3_e32 v154, v154
	v_mul_f32_e32 v236, v103, v145
	v_cvt_f32_ubyte2_e32 v145, v152
	v_rcp_f32_e32 v154, v154
	v_cndmask_b32_e64 v158, v158, v203, s[38:39]
	v_mul_f32_e32 v145, v145, v158
	v_mul_f32_e32 v237, v104, v145
	v_cvt_f32_ubyte3_e32 v145, v152
	v_cndmask_b32_e64 v152, v154, v203, s[38:39]
	v_mul_f32_e32 v145, v145, v152
	v_cvt_f32_ubyte0_e32 v152, v155
	v_rcp_f32_e32 v152, v152
	v_mul_f32_e32 v238, v105, v145
	v_cvt_f32_ubyte0_e32 v145, v153
	v_cndmask_b32_e64 v152, v152, v203, s[38:39]
	v_mul_f32_e32 v145, v145, v152
	v_cvt_f32_ubyte1_e32 v152, v155
	v_rcp_f32_e32 v152, v152
	v_cvt_f32_ubyte1_e32 v154, v153
	v_cvt_f32_ubyte2_e32 v158, v153
	v_cndmask_b32_e64 v152, v152, v203, s[38:39]
	v_mul_f32_e32 v152, v154, v152
	v_cvt_f32_ubyte2_e32 v154, v155
	v_cvt_f32_ubyte3_e32 v155, v155
	v_rcp_f32_e32 v154, v154
	v_rcp_f32_e32 v155, v155
	v_cvt_f32_ubyte3_e32 v153, v153
	v_lshl_add_u64 v[156:157], s[12:13], 0, v[156:157]
	v_cndmask_b32_e64 v154, v154, v203, s[38:39]
	v_cndmask_b32_e64 v155, v155, v203, s[38:39]
	v_lshl_add_u64 v[156:157], v[156:157], 0, s[30:31]
	v_mul_f32_e32 v154, v158, v154
	v_mul_f32_e32 v153, v153, v155
	v_lshl_add_u64 v[156:157], v[156:157], 0, v[0:1]
	v_mul_f32_e32 v145, v98, v145
	v_mul_f32_e32 v152, v99, v152
	v_mul_f32_e32 v154, v100, v154
	s_and_b64 vcc, exec, s[40:41]
	v_mul_f32_e32 v153, v101, v153
	s_cbranch_vccnz .LBB0_60
	v_cvt_pk_bf16_f32 v158, v235, v236
	v_cvt_pk_bf16_f32 v159, v237, v238
	v_cvt_pk_bf16_f32 v160, v145, v152
	v_cvt_pk_bf16_f32 v161, v154, v153
	global_store_dwordx4 v[156:157], v[158:161], off
	s_branch .LBB0_61

; __device__ __forceinline__ unsigned cvtpk(float lo, float hi) { unsigned r; asm volatile("v_cvt_pk_bf16_f32 %0, %1, %2" : "=v"(r) : "v"(lo), "v"(hi)); return r; }
;     __device__ __forceinline__ void operator()(f32x4 (&acc)[2][2][4][2], const pg8::Unit& u, int wr, int wc, int fr, int fq) const {
;     ...
;                 for (int bj = 0; bj < 2; ++bj) {
;                     f32x4 vv[2];
; #pragma unroll
;                     for (int n = 0; n < 2; ++n) {
;                         const unsigned a4 = ga[m][bj][n], b4 = gb[m][bj][n]; f32x4 v = acc[ai][bj][m][n];
; #pragma unroll
;                         for (int j = 0; j < 4; ++j) { const float ga_ = fmaxf((float)((a4 >> (8 * j)) & 255u), 1.f), gb_ = fmaxf((float)((b4 >> (8 * j)) & 255u), 1.f);
;                             v[j] *= last ? ga_ * (1.f / 255.f) : ga_ * __builtin_amdgcn_rcpf(gb_); }
;                         vv[n] = v; if (!last) acc[ai][bj][m][n] = v;
;                     }
;                     if (last) { u32x4 o = {cvtpk(vv[0][0], vv[0][1]), cvtpk(vv[0][2], vv[0][3]), cvtpk(vv[1][0], vv[1][1]), cvtpk(vv[1][2], vv[1][3])}; *(u32x4*)(op + bj * 128) = o; }
.LBB0_61:
	v_cvt_f32_ubyte0_e32 v145, v148
	v_rcp_f32_e32 v145, v145
	v_cvt_f32_ubyte0_e32 v152, v150
	v_cvt_f32_ubyte1_e32 v153, v148
	v_cndmask_b32_e64 v145, v145, v203, s[38:39]
	v_mul_f32_e32 v145, v152, v145
	v_max_f32_e32 v152, 1.0, v153
	v_rcp_f32_e32 v152, v152
	v_mul_f32_e32 v239, v70, v145
	v_cvt_f32_ubyte1_e32 v145, v150
	v_cndmask_b32_e64 v152, v152, v203, s[38:39]
	v_mul_f32_e32 v145, v145, v152
	v_cvt_f32_ubyte2_e32 v152, v148
	v_rcp_f32_e32 v152, v152
	v_cvt_f32_ubyte3_e32 v148, v148
	v_mul_f32_e32 v240, v71, v145
	v_cvt_f32_ubyte2_e32 v145, v150
	v_rcp_f32_e32 v148, v148
	v_cndmask_b32_e64 v152, v152, v203, s[38:39]
	v_mul_f32_e32 v145, v145, v152
	v_mul_f32_e32 v241, v72, v145
	v_cvt_f32_ubyte3_e32 v145, v150
	v_cndmask_b32_e64 v148, v148, v203, s[38:39]
	v_mul_f32_e32 v145, v145, v148
	v_cvt_f32_ubyte0_e32 v148, v149
	v_rcp_f32_e32 v148, v148
	v_mul_f32_e32 v242, v73, v145
	v_cvt_f32_ubyte0_e32 v145, v151
	v_cndmask_b32_e64 v148, v148, v203, s[38:39]
	v_mul_f32_e32 v145, v145, v148
	v_cvt_f32_ubyte1_e32 v148, v149
	v_rcp_f32_e32 v148, v148
	v_cvt_f32_ubyte1_e32 v150, v151
	v_cvt_f32_ubyte2_e32 v152, v151
	v_cndmask_b32_e64 v148, v148, v203, s[38:39]
	v_mul_f32_e32 v148, v150, v148
	v_cvt_f32_ubyte2_e32 v150, v149
	v_rcp_f32_e32 v150, v150
	v_cvt_f32_ubyte3_e32 v149, v149
	v_cndmask_b32_e64 v150, v150, v203, s[38:39]
	v_mul_f32_e32 v150, v152, v150
	v_rcp_f32_e32 v152, v149
	v_mul_f32_e32 v149, v68, v150
	v_cvt_f32_ubyte3_e32 v150, v151
	v_cndmask_b32_e64 v151, v152, v203, s[38:39]
	v_mul_f32_e32 v150, v150, v151
	v_mul_f32_e32 v145, v66, v145
	v_mul_f32_e32 v148, v67, v148
	s_and_b64 vcc, exec, s[40:41]
	v_mul_f32_e32 v150, v69, v150
	s_cbranch_vccnz .LBB0_63
	v_cvt_pk_bf16_f32 v152, v239, v240
	v_cvt_pk_bf16_f32 v153, v241, v242
	v_cvt_pk_bf16_f32 v154, v145, v148
	v_cvt_pk_bf16_f32 v155, v149, v150
	global_store_dwordx4 v[156:157], v[152:155], off offset:256
	s_branch .LBB0_64

; __device__ __forceinline__ unsigned cvtpk(float lo, float hi) { unsigned r; asm volatile("v_cvt_pk_bf16_f32 %0, %1, %2" : "=v"(r) : "v"(lo), "v"(hi)); return r; }
;     __device__ __forceinline__ void operator()(f32x4 (&acc)[2][2][4][2], const pg8::Unit& u, int wr, int wc, int fr, int fq) const {
;     ...
;                 for (int bj = 0; bj < 2; ++bj) {
;                     f32x4 vv[2];
; #pragma unroll
;                     for (int n = 0; n < 2; ++n) {
;                         const unsigned a4 = ga[m][bj][n], b4 = gb[m][bj][n]; f32x4 v = acc[ai][bj][m][n];
; #pragma unroll
;                         for (int j = 0; j < 4; ++j) { const float ga_ = fmaxf((float)((a4 >> (8 * j)) & 255u), 1.f), gb_ = fmaxf((float)((b4 >> (8 * j)) & 255u), 1.f);
;                             v[j] *= last ? ga_ * (1.f / 255.f) : ga_ * __builtin_amdgcn_rcpf(gb_); }
;                         vv[n] = v; if (!last) acc[ai][bj][m][n] = v;
;                     }
;                     if (last) { u32x4 o = {cvtpk(vv[0][0], vv[0][1]), cvtpk(vv[0][2], vv[0][3]), cvtpk(vv[1][0], vv[1][1]), cvtpk(vv[1][2], vv[1][3])}; *(u32x4*)(op + bj * 128) = o; }
.LBB0_80:
	s_waitcnt vmcnt(0)
	v_cvt_f32_ubyte0_e32 v194, v192
	v_rcp_f32_e32 v194, v194
	v_cvt_f32_ubyte0_e32 v195, v188
	v_cvt_f32_ubyte1_e32 v243, v188
	v_cndmask_b32_e64 v194, v194, v203, s[38:39]
	v_mul_f32_e32 v194, v195, v194
	v_cvt_f32_ubyte1_e32 v195, v192
	v_rcp_f32_e32 v195, v195
	v_cvt_f32_ubyte2_e32 v244, v188
	v_cndmask_b32_e64 v195, v195, v203, s[38:39]
	v_mul_f32_e32 v195, v243, v195
	v_cvt_f32_ubyte2_e32 v243, v192
	v_rcp_f32_e32 v243, v243
	v_cvt_f32_ubyte3_e32 v192, v192
	v_cvt_f32_ubyte3_e32 v188, v188
	v_cndmask_b32_e64 v243, v243, v203, s[38:39]
	v_mul_f32_e32 v243, v244, v243
	v_rcp_f32_e32 v244, v192
	v_mul_f32_e32 v192, v64, v243
	v_cvt_f32_ubyte1_e32 v245, v189
	v_cndmask_b32_e64 v243, v244, v203, s[38:39]
	v_mul_f32_e32 v188, v188, v243
	v_cvt_f32_ubyte0_e32 v243, v193
	v_rcp_f32_e32 v243, v243
	v_cvt_f32_ubyte0_e32 v244, v189
	v_cndmask_b32_e64 v243, v243, v203, s[38:39]
	v_mul_f32_e32 v243, v244, v243
	v_cvt_f32_ubyte1_e32 v244, v193
	v_rcp_f32_e32 v244, v244
	v_cvt_f32_ubyte2_e32 v246, v189
	v_lshlrev_b64 v[190:191], 11, v[190:191]
	v_cndmask_b32_e64 v244, v244, v203, s[38:39]
	v_mul_f32_e32 v244, v245, v244
	v_cvt_f32_ubyte2_e32 v245, v193
	v_rcp_f32_e32 v245, v245
	v_cvt_f32_ubyte3_e32 v193, v193
	v_cvt_f32_ubyte3_e32 v189, v189
	v_cndmask_b32_e64 v245, v245, v203, s[38:39]
	v_mul_f32_e32 v245, v246, v245
	v_rcp_f32_e32 v246, v193
	v_lshl_add_u64 v[190:191], s[12:13], 0, v[190:191]
	v_mul_f32_e32 v193, v60, v245
	v_cndmask_b32_e64 v245, v246, v203, s[38:39]
	v_lshl_add_u64 v[190:191], v[190:191], 0, s[30:31]
	v_mul_f32_e32 v189, v189, v245
	v_lshl_add_u64 v[190:191], v[190:191], 0, v[0:1]
	v_mul_f32_e32 v194, v62, v194
	v_mul_f32_e32 v195, v63, v195
	v_mul_f32_e32 v188, v65, v188
	v_mul_f32_e32 v243, v58, v243
	v_mul_f32_e32 v244, v59, v244
	s_and_b64 vcc, exec, s[40:41]
	v_mul_f32_e32 v189, v61, v189
	s_cbranch_vccnz .LBB0_82
	v_cvt_pk_bf16_f32 v246, v194, v195
	v_cvt_pk_bf16_f32 v247, v192, v188
	v_cvt_pk_bf16_f32 v248, v243, v244
	v_cvt_pk_bf16_f32 v249, v193, v189
	global_store_dwordx4 v[190:191], v[246:249], off
	s_branch .LBB0_83

; __device__ __forceinline__ unsigned cvtpk(float lo, float hi) { unsigned r; asm volatile("v_cvt_pk_bf16_f32 %0, %1, %2" : "=v"(r) : "v"(lo), "v"(hi)); return r; }
;     __device__ __forceinline__ void operator()(f32x4 (&acc)[2][2][4][2], const pg8::Unit& u, int wr, int wc, int fr, int fq) const {
;     ...
;                 for (int bj = 0; bj < 2; ++bj) {
;                     f32x4 vv[2];
; #pragma unroll
;                     for (int n = 0; n < 2; ++n) {
;                         const unsigned a4 = ga[m][bj][n], b4 = gb[m][bj][n]; f32x4 v = acc[ai][bj][m][n];
; #pragma unroll
;                         for (int j = 0; j < 4; ++j) { const float ga_ = fmaxf((float)((a4 >> (8 * j)) & 255u), 1.f), gb_ = fmaxf((float)((b4 >> (8 * j)) & 255u), 1.f);
;                             v[j] *= last ? ga_ * (1.f / 255.f) : ga_ * __builtin_amdgcn_rcpf(gb_); }
;                         vv[n] = v; if (!last) acc[ai][bj][m][n] = v;
;                     }
;                     if (last) { u32x4 o = {cvtpk(vv[0][0], vv[0][1]), cvtpk(vv[0][2], vv[0][3]), cvtpk(vv[1][0], vv[1][1]), cvtpk(vv[1][2], vv[1][3])}; *(u32x4*)(op + bj * 128) = o; }
.LBB0_83:
	v_cvt_f32_ubyte0_e32 v189, v184
	v_rcp_f32_e32 v189, v189
	v_cvt_f32_ubyte0_e32 v193, v186
	v_cvt_f32_ubyte1_e32 v243, v184
	v_cndmask_b32_e64 v189, v189, v203, s[38:39]
	v_mul_f32_e32 v189, v193, v189
	v_max_f32_e32 v193, 1.0, v243
	v_rcp_f32_e32 v193, v193
	v_cvt_f32_ubyte1_e32 v243, v186
	v_cvt_f32_ubyte2_e32 v244, v186
	v_cndmask_b32_e64 v193, v193, v203, s[38:39]
	v_mul_f32_e32 v193, v243, v193
	v_cvt_f32_ubyte2_e32 v243, v184
	v_rcp_f32_e32 v243, v243
	v_cvt_f32_ubyte3_e32 v184, v184
	v_cndmask_b32_e64 v243, v243, v203, s[38:39]
	v_mul_f32_e32 v243, v244, v243
	v_rcp_f32_e32 v244, v184
	v_cvt_f32_ubyte3_e32 v186, v186
	v_mul_f32_e32 v184, v32, v243
	v_cndmask_b32_e64 v243, v244, v203, s[38:39]
	v_mul_f32_e32 v186, v186, v243
	v_cvt_f32_ubyte0_e32 v243, v185
	v_rcp_f32_e32 v243, v243
	v_cvt_f32_ubyte0_e32 v244, v187
	v_cvt_f32_ubyte1_e32 v245, v187
	v_cndmask_b32_e64 v243, v243, v203, s[38:39]
	v_mul_f32_e32 v243, v244, v243
	v_cvt_f32_ubyte1_e32 v244, v185
	v_rcp_f32_e32 v244, v244
	v_cvt_f32_ubyte2_e32 v246, v187
	v_cndmask_b32_e64 v244, v244, v203, s[38:39]
	v_mul_f32_e32 v244, v245, v244
	v_cvt_f32_ubyte2_e32 v245, v185
	v_rcp_f32_e32 v245, v245
	v_cvt_f32_ubyte3_e32 v185, v185
	v_cvt_f32_ubyte3_e32 v187, v187
	v_cndmask_b32_e64 v245, v245, v203, s[38:39]
	v_mul_f32_e32 v245, v246, v245
	v_rcp_f32_e32 v246, v185
	v_mul_f32_e32 v185, v28, v245
	v_mul_f32_e32 v189, v30, v189
	v_cndmask_b32_e64 v245, v246, v203, s[38:39]
	v_mul_f32_e32 v187, v187, v245
	v_mul_f32_e32 v193, v31, v193
	v_mul_f32_e32 v186, v33, v186
	v_mul_f32_e32 v243, v26, v243
	v_mul_f32_e32 v244, v27, v244
	s_and_b64 vcc, exec, s[40:41]
	v_mul_f32_e32 v187, v29, v187
	s_cbranch_vccnz .LBB0_85
	v_cvt_pk_bf16_f32 v246, v189, v193
	v_cvt_pk_bf16_f32 v247, v184, v186
	v_cvt_pk_bf16_f32 v248, v243, v244
	v_cvt_pk_bf16_f32 v249, v185, v187
	global_store_dwordx4 v[190:191], v[246:249], off offset:256
	s_branch .LBB0_86

; __device__ __forceinline__ unsigned cvtpk(float lo, float hi) { unsigned r; asm volatile("v_cvt_pk_bf16_f32 %0, %1, %2" : "=v"(r) : "v"(lo), "v"(hi)); return r; }
;     __device__ __forceinline__ void operator()(f32x4 (&acc)[2][2][4][2], const pg8::Unit& u, int wr, int wc, int fr, int fq) const {
;     ...
;                 for (int bj = 0; bj < 2; ++bj) {
;                     f32x4 vv[2];
; #pragma unroll
;                     for (int n = 0; n < 2; ++n) {
;                         const unsigned a4 = ga[m][bj][n], b4 = gb[m][bj][n]; f32x4 v = acc[ai][bj][m][n];
; #pragma unroll
;                         for (int j = 0; j < 4; ++j) { const float ga_ = fmaxf((float)((a4 >> (8 * j)) & 255u), 1.f), gb_ = fmaxf((float)((b4 >> (8 * j)) & 255u), 1.f);
;                             v[j] *= last ? ga_ * (1.f / 255.f) : ga_ * __builtin_amdgcn_rcpf(gb_); }
;                         vv[n] = v; if (!last) acc[ai][bj][m][n] = v;
;                     }
;                     if (last) { u32x4 o = {cvtpk(vv[0][0], vv[0][1]), cvtpk(vv[0][2], vv[0][3]), cvtpk(vv[1][0], vv[1][1]), cvtpk(vv[1][2], vv[1][3])}; *(u32x4*)(op + bj * 128) = o; }
.LBB0_86:
	v_cvt_f32_ubyte0_e32 v185, v180
	v_rcp_f32_e32 v185, v185
	v_cvt_f32_ubyte0_e32 v187, v178
	v_cvt_f32_ubyte1_e32 v190, v178
	v_cndmask_b32_e64 v185, v185, v203, s[38:39]
	v_mul_f32_e32 v185, v187, v185
	v_cvt_f32_ubyte1_e32 v187, v180
	v_rcp_f32_e32 v187, v187
	v_cvt_f32_ubyte2_e32 v191, v178
	v_cndmask_b32_e64 v187, v187, v203, s[38:39]
	v_mul_f32_e32 v187, v190, v187
	v_cvt_f32_ubyte2_e32 v190, v180
	v_rcp_f32_e32 v190, v190
	v_cvt_f32_ubyte3_e32 v180, v180
	v_cvt_f32_ubyte3_e32 v178, v178
	v_cndmask_b32_e64 v190, v190, v203, s[38:39]
	v_mul_f32_e32 v190, v191, v190
	v_rcp_f32_e32 v191, v180
	v_mul_f32_e32 v180, v56, v190
	v_cvt_f32_ubyte1_e32 v243, v179
	v_cndmask_b32_e64 v190, v191, v203, s[38:39]
	v_mul_f32_e32 v178, v178, v190
	v_cvt_f32_ubyte0_e32 v190, v181
	v_rcp_f32_e32 v190, v190
	v_cvt_f32_ubyte0_e32 v191, v179
	v_cndmask_b32_e64 v190, v190, v203, s[38:39]
	v_mul_f32_e32 v190, v191, v190
	v_cvt_f32_ubyte1_e32 v191, v181
	v_rcp_f32_e32 v191, v191
	v_cvt_f32_ubyte2_e32 v244, v179
	v_lshlrev_b64 v[182:183], 11, v[182:183]
	v_cndmask_b32_e64 v191, v191, v203, s[38:39]
	v_mul_f32_e32 v191, v243, v191
	v_cvt_f32_ubyte2_e32 v243, v181
	v_rcp_f32_e32 v243, v243
	v_cvt_f32_ubyte3_e32 v181, v181
	v_cvt_f32_ubyte3_e32 v179, v179
	v_cndmask_b32_e64 v243, v243, v203, s[38:39]
	v_mul_f32_e32 v243, v244, v243
	v_rcp_f32_e32 v244, v181
	v_lshl_add_u64 v[182:183], s[12:13], 0, v[182:183]
	v_mul_f32_e32 v181, v52, v243
	v_cndmask_b32_e64 v243, v244, v203, s[38:39]
	v_lshl_add_u64 v[182:183], v[182:183], 0, s[30:31]
	v_mul_f32_e32 v179, v179, v243
	v_lshl_add_u64 v[182:183], v[182:183], 0, v[0:1]
	v_mul_f32_e32 v185, v54, v185
	v_mul_f32_e32 v187, v55, v187
	v_mul_f32_e32 v178, v57, v178
	v_mul_f32_e32 v190, v50, v190
	v_mul_f32_e32 v191, v51, v191
	s_and_b64 vcc, exec, s[40:41]
	v_mul_f32_e32 v179, v53, v179
	s_cbranch_vccnz .LBB0_88
	v_cvt_pk_bf16_f32 v244, v185, v187
	v_cvt_pk_bf16_f32 v245, v180, v178
	v_cvt_pk_bf16_f32 v246, v190, v191
	v_cvt_pk_bf16_f32 v247, v181, v179
	global_store_dwordx4 v[182:183], v[244:247], off
	s_branch .LBB0_89

; __device__ __forceinline__ unsigned cvtpk(float lo, float hi) { unsigned r; asm volatile("v_cvt_pk_bf16_f32 %0, %1, %2" : "=v"(r) : "v"(lo), "v"(hi)); return r; }
;     __device__ __forceinline__ void operator()(f32x4 (&acc)[2][2][4][2], const pg8::Unit& u, int wr, int wc, int fr, int fq) const {
;     ...
;                         const unsigned a4 = ga[m][bj][n], b4 = gb[m][bj][n]; f32x4 v = acc[ai][bj][m][n];
; #pragma unroll
;                         for (int j = 0; j < 4; ++j) { const float ga_ = fmaxf((float)((a4 >> (8 * j)) & 255u), 1.f), gb_ = fmaxf((float)((b4 >> (8 * j)) & 255u), 1.f);
;                             v[j] *= last ? ga_ * (1.f / 255.f) : ga_ * __builtin_amdgcn_rcpf(gb_); }
;                         vv[n] = v; if (!last) acc[ai][bj][m][n] = v;
;                     }
;                     if (last) { u32x4 o = {cvtpk(vv[0][0], vv[0][1]), cvtpk(vv[0][2], vv[0][3]), cvtpk(vv[1][0], vv[1][1]), cvtpk(vv[1][2], vv[1][3])}; *(u32x4*)(op + bj * 128) = o; }
.LBB0_89:
	v_cvt_f32_ubyte0_e32 v179, v174
	v_rcp_f32_e32 v179, v179
	v_cvt_f32_ubyte0_e32 v181, v176
	v_cvt_f32_ubyte1_e32 v190, v174
	v_cndmask_b32_e64 v179, v179, v203, s[38:39]
	v_mul_f32_e32 v179, v181, v179
	v_max_f32_e32 v181, 1.0, v190
	v_rcp_f32_e32 v181, v181
	v_cvt_f32_ubyte1_e32 v190, v176
	v_cvt_f32_ubyte2_e32 v191, v176
	v_cndmask_b32_e64 v181, v181, v203, s[38:39]
	v_mul_f32_e32 v181, v190, v181
	v_cvt_f32_ubyte2_e32 v190, v174
	v_rcp_f32_e32 v190, v190
	v_cvt_f32_ubyte3_e32 v174, v174
	v_cndmask_b32_e64 v190, v190, v203, s[38:39]
	v_mul_f32_e32 v190, v191, v190
	v_rcp_f32_e32 v191, v174
	v_cvt_f32_ubyte3_e32 v176, v176
	v_mul_f32_e32 v174, v24, v190
	v_cndmask_b32_e64 v190, v191, v203, s[38:39]
	v_mul_f32_e32 v176, v176, v190
	v_cvt_f32_ubyte0_e32 v190, v175
	v_rcp_f32_e32 v190, v190
	v_cvt_f32_ubyte0_e32 v191, v177
	v_cvt_f32_ubyte1_e32 v243, v177
	v_cndmask_b32_e64 v190, v190, v203, s[38:39]
	v_mul_f32_e32 v190, v191, v190
	v_cvt_f32_ubyte1_e32 v191, v175
	v_rcp_f32_e32 v191, v191
	v_cvt_f32_ubyte2_e32 v244, v177
	v_cndmask_b32_e64 v191, v191, v203, s[38:39]
	v_mul_f32_e32 v191, v243, v191
	v_cvt_f32_ubyte2_e32 v243, v175
	v_rcp_f32_e32 v243, v243
	v_cvt_f32_ubyte3_e32 v175, v175
	v_cvt_f32_ubyte3_e32 v177, v177
	v_cndmask_b32_e64 v243, v243, v203, s[38:39]
	v_mul_f32_e32 v243, v244, v243
	v_rcp_f32_e32 v244, v175
	v_mul_f32_e32 v175, v20, v243
	v_mul_f32_e32 v179, v22, v179
	v_cndmask_b32_e64 v243, v244, v203, s[38:39]
	v_mul_f32_e32 v177, v177, v243
	v_mul_f32_e32 v181, v23, v181
	v_mul_f32_e32 v176, v25, v176
	v_mul_f32_e32 v190, v18, v190
	v_mul_f32_e32 v191, v19, v191
	s_and_b64 vcc, exec, s[40:41]
	v_mul_f32_e32 v177, v21, v177
	s_cbranch_vccnz .LBB0_91
	v_cvt_pk_bf16_f32 v244, v179, v181
	v_cvt_pk_bf16_f32 v245, v174, v176
	v_cvt_pk_bf16_f32 v246, v190, v191
	v_cvt_pk_bf16_f32 v247, v175, v177
	global_store_dwordx4 v[182:183], v[244:247], off offset:256
	s_branch .LBB0_92

; __device__ __forceinline__ unsigned cvtpk(float lo, float hi) { unsigned r; asm volatile("v_cvt_pk_bf16_f32 %0, %1, %2" : "=v"(r) : "v"(lo), "v"(hi)); return r; }
;     __device__ __forceinline__ void operator()(f32x4 (&acc)[2][2][4][2], const pg8::Unit& u, int wr, int wc, int fr, int fq) const {
;     ...
;                         const unsigned a4 = ga[m][bj][n], b4 = gb[m][bj][n]; f32x4 v = acc[ai][bj][m][n];
; #pragma unroll
;                         for (int j = 0; j < 4; ++j) { const float ga_ = fmaxf((float)((a4 >> (8 * j)) & 255u), 1.f), gb_ = fmaxf((float)((b4 >> (8 * j)) & 255u), 1.f);
;                             v[j] *= last ? ga_ * (1.f / 255.f) : ga_ * __builtin_amdgcn_rcpf(gb_); }
;                         vv[n] = v; if (!last) acc[ai][bj][m][n] = v;
;                     }
;                     if (last) { u32x4 o = {cvtpk(vv[0][0], vv[0][1]), cvtpk(vv[0][2], vv[0][3]), cvtpk(vv[1][0], vv[1][1]), cvtpk(vv[1][2], vv[1][3])}; *(u32x4*)(op + bj * 128) = o; }
.LBB0_92:
	v_cvt_f32_ubyte0_e32 v175, v160
	v_rcp_f32_e32 v175, v175
	v_cvt_f32_ubyte0_e32 v177, v158
	v_cvt_f32_ubyte1_e32 v182, v158
	v_cndmask_b32_e64 v175, v175, v203, s[38:39]
	v_mul_f32_e32 v175, v177, v175
	v_cvt_f32_ubyte1_e32 v177, v160
	v_rcp_f32_e32 v177, v177
	v_cvt_f32_ubyte2_e32 v183, v158
	v_cndmask_b32_e64 v177, v177, v203, s[38:39]
	v_mul_f32_e32 v177, v182, v177
	v_cvt_f32_ubyte2_e32 v182, v160
	v_rcp_f32_e32 v182, v182
	v_cvt_f32_ubyte3_e32 v160, v160
	v_cvt_f32_ubyte3_e32 v158, v158
	v_cndmask_b32_e64 v182, v182, v203, s[38:39]
	v_mul_f32_e32 v182, v183, v182
	v_rcp_f32_e32 v183, v160
	v_mul_f32_e32 v160, v48, v182
	v_cvt_f32_ubyte1_e32 v190, v159
	v_cndmask_b32_e64 v182, v183, v203, s[38:39]
	v_mul_f32_e32 v158, v158, v182
	v_cvt_f32_ubyte0_e32 v182, v161
	v_rcp_f32_e32 v182, v182
	v_cvt_f32_ubyte0_e32 v183, v159
	v_cndmask_b32_e64 v182, v182, v203, s[38:39]
	v_mul_f32_e32 v182, v183, v182
	v_cvt_f32_ubyte1_e32 v183, v161
	v_rcp_f32_e32 v183, v183
	v_cvt_f32_ubyte2_e32 v191, v159
	v_lshlrev_b64 v[172:173], 11, v[172:173]
	v_cndmask_b32_e64 v183, v183, v203, s[38:39]
	v_mul_f32_e32 v183, v190, v183
	v_cvt_f32_ubyte2_e32 v190, v161
	v_rcp_f32_e32 v190, v190
	v_cvt_f32_ubyte3_e32 v161, v161
	v_cvt_f32_ubyte3_e32 v159, v159
	v_cndmask_b32_e64 v190, v190, v203, s[38:39]
	v_mul_f32_e32 v190, v191, v190
	v_rcp_f32_e32 v191, v161
	v_lshl_add_u64 v[172:173], s[12:13], 0, v[172:173]
	v_mul_f32_e32 v161, v44, v190
	v_cndmask_b32_e64 v190, v191, v203, s[38:39]
	v_lshl_add_u64 v[172:173], v[172:173], 0, s[30:31]
	v_mul_f32_e32 v159, v159, v190
	v_lshl_add_u64 v[172:173], v[172:173], 0, v[0:1]
	v_mul_f32_e32 v175, v46, v175
	v_mul_f32_e32 v177, v47, v177
	v_mul_f32_e32 v158, v49, v158
	v_mul_f32_e32 v182, v42, v182
	v_mul_f32_e32 v183, v43, v183
	s_and_b64 vcc, exec, s[40:41]
	v_mul_f32_e32 v159, v45, v159
	s_cbranch_vccnz .LBB0_94
	v_cvt_pk_bf16_f32 v244, v175, v177
	v_cvt_pk_bf16_f32 v245, v160, v158
	v_cvt_pk_bf16_f32 v246, v182, v183
	v_cvt_pk_bf16_f32 v247, v161, v159
	global_store_dwordx4 v[172:173], v[244:247], off
	s_branch .LBB0_95

; __device__ __forceinline__ unsigned cvtpk(float lo, float hi) { unsigned r; asm volatile("v_cvt_pk_bf16_f32 %0, %1, %2" : "=v"(r) : "v"(lo), "v"(hi)); return r; }
;     __device__ __forceinline__ void operator()(f32x4 (&acc)[2][2][4][2], const pg8::Unit& u, int wr, int wc, int fr, int fq) const {
;     ...
;                         const unsigned a4 = ga[m][bj][n], b4 = gb[m][bj][n]; f32x4 v = acc[ai][bj][m][n];
; #pragma unroll
;                         for (int j = 0; j < 4; ++j) { const float ga_ = fmaxf((float)((a4 >> (8 * j)) & 255u), 1.f), gb_ = fmaxf((float)((b4 >> (8 * j)) & 255u), 1.f);
;                             v[j] *= last ? ga_ * (1.f / 255.f) : ga_ * __builtin_amdgcn_rcpf(gb_); }
;                         vv[n] = v; if (!last) acc[ai][bj][m][n] = v;
;                     }
;                     if (last) { u32x4 o = {cvtpk(vv[0][0], vv[0][1]), cvtpk(vv[0][2], vv[0][3]), cvtpk(vv[1][0], vv[1][1]), cvtpk(vv[1][2], vv[1][3])}; *(u32x4*)(op + bj * 128) = o; }
.LBB0_95:
	v_cvt_f32_ubyte0_e32 v159, v154
	v_rcp_f32_e32 v159, v159
	v_cvt_f32_ubyte0_e32 v161, v156
	v_cvt_f32_ubyte1_e32 v182, v154
	v_cndmask_b32_e64 v159, v159, v203, s[38:39]
	v_mul_f32_e32 v159, v161, v159
	v_max_f32_e32 v161, 1.0, v182
	v_rcp_f32_e32 v161, v161
	v_cvt_f32_ubyte1_e32 v182, v156
	v_cvt_f32_ubyte2_e32 v183, v156
	v_cndmask_b32_e64 v161, v161, v203, s[38:39]
	v_mul_f32_e32 v161, v182, v161
	v_cvt_f32_ubyte2_e32 v182, v154
	v_rcp_f32_e32 v182, v182
	v_cvt_f32_ubyte3_e32 v154, v154
	v_cndmask_b32_e64 v182, v182, v203, s[38:39]
	v_mul_f32_e32 v182, v183, v182
	v_rcp_f32_e32 v183, v154
	v_cvt_f32_ubyte3_e32 v156, v156
	v_mul_f32_e32 v154, v16, v182
	v_cndmask_b32_e64 v182, v183, v203, s[38:39]
	v_mul_f32_e32 v156, v156, v182
	v_cvt_f32_ubyte0_e32 v182, v155
	v_rcp_f32_e32 v182, v182
	v_cvt_f32_ubyte0_e32 v183, v157
	v_cvt_f32_ubyte1_e32 v190, v157
	v_cndmask_b32_e64 v182, v182, v203, s[38:39]
	v_mul_f32_e32 v182, v183, v182
	v_cvt_f32_ubyte1_e32 v183, v155
	v_rcp_f32_e32 v183, v183
	v_cvt_f32_ubyte2_e32 v191, v157
	v_cndmask_b32_e64 v183, v183, v203, s[38:39]
	v_mul_f32_e32 v183, v190, v183
	v_cvt_f32_ubyte2_e32 v190, v155
	v_rcp_f32_e32 v190, v190
	v_cvt_f32_ubyte3_e32 v155, v155
	v_cvt_f32_ubyte3_e32 v157, v157
	v_cndmask_b32_e64 v190, v190, v203, s[38:39]
	v_mul_f32_e32 v190, v191, v190
	v_rcp_f32_e32 v191, v155
	v_mul_f32_e32 v155, v12, v190
	v_mul_f32_e32 v159, v14, v159
	v_cndmask_b32_e64 v190, v191, v203, s[38:39]
	v_mul_f32_e32 v157, v157, v190
	v_mul_f32_e32 v161, v15, v161
	v_mul_f32_e32 v156, v17, v156
	v_mul_f32_e32 v182, v10, v182
	v_mul_f32_e32 v183, v11, v183
	s_and_b64 vcc, exec, s[40:41]
	v_mul_f32_e32 v157, v13, v157
	s_cbranch_vccnz .LBB0_97
	v_cvt_pk_bf16_f32 v244, v159, v161
	v_cvt_pk_bf16_f32 v245, v154, v156
	v_cvt_pk_bf16_f32 v246, v182, v183
	v_cvt_pk_bf16_f32 v247, v155, v157
	global_store_dwordx4 v[172:173], v[244:247], off offset:256
	s_branch .LBB0_98

; __device__ __forceinline__ unsigned cvtpk(float lo, float hi) { unsigned r; asm volatile("v_cvt_pk_bf16_f32 %0, %1, %2" : "=v"(r) : "v"(lo), "v"(hi)); return r; }
;     __device__ __forceinline__ void operator()(f32x4 (&acc)[2][2][4][2], const pg8::Unit& u, int wr, int wc, int fr, int fq) const {
;     ...
;                         const unsigned a4 = ga[m][bj][n], b4 = gb[m][bj][n]; f32x4 v = acc[ai][bj][m][n];
; #pragma unroll
;                         for (int j = 0; j < 4; ++j) { const float ga_ = fmaxf((float)((a4 >> (8 * j)) & 255u), 1.f), gb_ = fmaxf((float)((b4 >> (8 * j)) & 255u), 1.f);
;                             v[j] *= last ? ga_ * (1.f / 255.f) : ga_ * __builtin_amdgcn_rcpf(gb_); }
;                         vv[n] = v; if (!last) acc[ai][bj][m][n] = v;
;                     }
;                     if (last) { u32x4 o = {cvtpk(vv[0][0], vv[0][1]), cvtpk(vv[0][2], vv[0][3]), cvtpk(vv[1][0], vv[1][1]), cvtpk(vv[1][2], vv[1][3])}; *(u32x4*)(op + bj * 128) = o; }
.LBB0_98:
	v_cvt_f32_ubyte0_e32 v155, v150
	v_rcp_f32_e32 v155, v155
	v_cvt_f32_ubyte0_e32 v157, v148
	v_cvt_f32_ubyte1_e32 v172, v148
	v_cndmask_b32_e64 v155, v155, v203, s[38:39]
	v_mul_f32_e32 v155, v157, v155
	v_cvt_f32_ubyte1_e32 v157, v150
	v_rcp_f32_e32 v157, v157
	v_cvt_f32_ubyte2_e32 v173, v148
	v_cndmask_b32_e64 v157, v157, v203, s[38:39]
	v_mul_f32_e32 v157, v172, v157
	v_cvt_f32_ubyte2_e32 v172, v150
	v_rcp_f32_e32 v172, v172
	v_cvt_f32_ubyte3_e32 v150, v150
	v_cvt_f32_ubyte3_e32 v148, v148
	v_cndmask_b32_e64 v172, v172, v203, s[38:39]
	v_mul_f32_e32 v172, v173, v172
	v_rcp_f32_e32 v173, v150
	v_mul_f32_e32 v150, v40, v172
	v_cvt_f32_ubyte1_e32 v182, v149
	v_cndmask_b32_e64 v172, v173, v203, s[38:39]
	v_mul_f32_e32 v148, v148, v172
	v_cvt_f32_ubyte0_e32 v172, v151
	v_rcp_f32_e32 v172, v172
	v_cvt_f32_ubyte0_e32 v173, v149
	v_cndmask_b32_e64 v172, v172, v203, s[38:39]
	v_mul_f32_e32 v172, v173, v172
	v_cvt_f32_ubyte1_e32 v173, v151
	v_rcp_f32_e32 v173, v173
	v_cvt_f32_ubyte2_e32 v183, v149
	v_lshlrev_b64 v[152:153], 11, v[152:153]
	v_cndmask_b32_e64 v173, v173, v203, s[38:39]
	v_mul_f32_e32 v173, v182, v173
	v_cvt_f32_ubyte2_e32 v182, v151
	v_rcp_f32_e32 v182, v182
	v_cvt_f32_ubyte3_e32 v151, v151
	v_cvt_f32_ubyte3_e32 v149, v149
	v_cndmask_b32_e64 v182, v182, v203, s[38:39]
	v_mul_f32_e32 v182, v183, v182
	v_rcp_f32_e32 v183, v151
	v_lshl_add_u64 v[152:153], s[12:13], 0, v[152:153]
	v_mul_f32_e32 v151, v36, v182
	v_cndmask_b32_e64 v182, v183, v203, s[38:39]
	v_lshl_add_u64 v[152:153], v[152:153], 0, s[30:31]
	v_mul_f32_e32 v149, v149, v182
	v_lshl_add_u64 v[152:153], v[152:153], 0, v[0:1]
	v_mul_f32_e32 v155, v38, v155
	v_mul_f32_e32 v157, v39, v157
	v_mul_f32_e32 v148, v41, v148
	v_mul_f32_e32 v172, v34, v172
	v_mul_f32_e32 v173, v35, v173
	s_and_b64 vcc, exec, s[40:41]
	v_mul_f32_e32 v149, v37, v149
	s_cbranch_vccnz .LBB0_100
	v_cvt_pk_bf16_f32 v244, v155, v157
	v_cvt_pk_bf16_f32 v245, v150, v148
	v_cvt_pk_bf16_f32 v246, v172, v173
	v_cvt_pk_bf16_f32 v247, v151, v149
	global_store_dwordx4 v[152:153], v[244:247], off
	s_branch .LBB0_101

; __device__ __forceinline__ unsigned cvtpk(float lo, float hi) { unsigned r; asm volatile("v_cvt_pk_bf16_f32 %0, %1, %2" : "=v"(r) : "v"(lo), "v"(hi)); return r; }
;     __device__ __forceinline__ void operator()(f32x4 (&acc)[2][2][4][2], const pg8::Unit& u, int wr, int wc, int fr, int fq) const {
;     ...
;                         const unsigned a4 = ga[m][bj][n], b4 = gb[m][bj][n]; f32x4 v = acc[ai][bj][m][n];
; #pragma unroll
;                         for (int j = 0; j < 4; ++j) { const float ga_ = fmaxf((float)((a4 >> (8 * j)) & 255u), 1.f), gb_ = fmaxf((float)((b4 >> (8 * j)) & 255u), 1.f);
;                             v[j] *= last ? ga_ * (1.f / 255.f) : ga_ * __builtin_amdgcn_rcpf(gb_); }
;                         vv[n] = v; if (!last) acc[ai][bj][m][n] = v;
;                     }
;                     if (last) { u32x4 o = {cvtpk(vv[0][0], vv[0][1]), cvtpk(vv[0][2], vv[0][3]), cvtpk(vv[1][0], vv[1][1]), cvtpk(vv[1][2], vv[1][3])}; *(u32x4*)(op + bj * 128) = o; }
.LBB0_101:
	v_cvt_f32_ubyte0_e32 v149, v144
	v_rcp_f32_e32 v149, v149
	v_cvt_f32_ubyte0_e32 v151, v146
	v_cvt_f32_ubyte1_e32 v172, v144
	v_cndmask_b32_e64 v149, v149, v203, s[38:39]
	v_mul_f32_e32 v149, v151, v149
	v_max_f32_e32 v151, 1.0, v172
	v_rcp_f32_e32 v151, v151
	v_cvt_f32_ubyte1_e32 v172, v146
	v_cvt_f32_ubyte2_e32 v173, v146
	v_cndmask_b32_e64 v151, v151, v203, s[38:39]
	v_mul_f32_e32 v151, v172, v151
	v_cvt_f32_ubyte2_e32 v172, v144
	v_rcp_f32_e32 v172, v172
	v_cvt_f32_ubyte3_e32 v144, v144
	v_cndmask_b32_e64 v172, v172, v203, s[38:39]
	v_mul_f32_e32 v172, v173, v172
	v_rcp_f32_e32 v173, v144
	v_cvt_f32_ubyte3_e32 v146, v146
	v_mul_f32_e32 v144, v8, v172
	v_cndmask_b32_e64 v172, v173, v203, s[38:39]
	v_mul_f32_e32 v146, v146, v172
	v_cvt_f32_ubyte0_e32 v172, v145
	v_rcp_f32_e32 v172, v172
	v_cvt_f32_ubyte0_e32 v173, v147
	v_cvt_f32_ubyte1_e32 v182, v147
	v_cndmask_b32_e64 v172, v172, v203, s[38:39]
	v_mul_f32_e32 v172, v173, v172
	v_cvt_f32_ubyte1_e32 v173, v145
	v_rcp_f32_e32 v173, v173
	v_cvt_f32_ubyte2_e32 v183, v147
	v_cndmask_b32_e64 v173, v173, v203, s[38:39]
	v_mul_f32_e32 v173, v182, v173
	v_cvt_f32_ubyte2_e32 v182, v145
	v_rcp_f32_e32 v182, v182
	v_cvt_f32_ubyte3_e32 v145, v145
	v_cvt_f32_ubyte3_e32 v147, v147
	v_cndmask_b32_e64 v182, v182, v203, s[38:39]
	v_mul_f32_e32 v182, v183, v182
	v_rcp_f32_e32 v183, v145
	v_mul_f32_e32 v145, v4, v182
	v_mul_f32_e32 v149, v6, v149
	v_cndmask_b32_e64 v182, v183, v203, s[38:39]
	v_mul_f32_e32 v147, v147, v182
	v_mul_f32_e32 v151, v7, v151
	v_mul_f32_e32 v146, v9, v146
	v_mul_f32_e32 v172, v2, v172
	v_mul_f32_e32 v173, v3, v173
	s_and_b64 vcc, exec, s[40:41]
	v_mul_f32_e32 v147, v5, v147
	s_cbranch_vccnz .LBB0_103
	v_cvt_pk_bf16_f32 v244, v149, v151
	v_cvt_pk_bf16_f32 v245, v144, v146
	v_cvt_pk_bf16_f32 v246, v172, v173
	v_cvt_pk_bf16_f32 v247, v145, v147
	global_store_dwordx4 v[152:153], v[244:247], off offset:256
	s_mov_b64 s[20:21], -1
	s_and_b64 vcc, exec, s[34:35]
	s_cbranch_vccz .LBB0_21
	s_branch .LBB0_104

; __device__ __forceinline__ float sigmoidf_(float x) { return __builtin_amdgcn_rcpf(1.f + __expf(-x)); }
;     __device__ __forceinline__ void operator()(f32x4 (&acc)[2][2][4][2], const pg8::Unit& u, int wr, int wc, int fr, int fq) const {
;     ...
;             for (int ai = 0; ai < 2; ++ai)
; #pragma unroll
;                 for (int m = 0; m < 4; ++m) {
;                     unsigned char* gp = gq + (size_t)(row0 + ai * 128 + m * 16) * 4096 + (u.pn - 28) * 256 + cin;
; #pragma unroll
;                     for (int bj = 0; bj < 2; ++bj) { unsigned w2[2];
; #pragma unroll
;                         for (int n = 0; n < 2; ++n) {
;                             const f32x4 v = acc[ai][bj][m][n];
;                             const unsigned b0 = (unsigned)(sigmoidf_(v[0]) * 255.f + 0.5f), b1 = (unsigned)(sigmoidf_(v[1]) * 255.f + 0.5f),
;                                            b2 = (unsigned)(sigmoidf_(v[2]) * 255.f + 0.5f), b3 = (unsigned)(sigmoidf_(v[3]) * 255.f + 0.5f);
;                             w2[n] = b0 | (b1 << 8) | (b2 << 16) | (b3 << 24);
;                         }
;                         u32x2 o = {w2[0], w2[1]}; *(u32x2*)(gp + bj * 128) = o; }
.LBB0_1065:
	s_and_b64 vcc, exec, s[0:1]
	s_cbranch_vccz .LBB0_1067
	v_readlane_b32 s52, v251, 1
	v_readlane_b32 s53, v251, 2
	v_readlane_b32 s54, v251, 3
	v_readlane_b32 s55, v251, 4
	v_readlane_b32 s56, v251, 5
	v_readlane_b32 s57, v251, 6
	v_readlane_b32 s58, v251, 7
	v_readlane_b32 s59, v251, 8
	v_ashrrev_i32_e32 v155, 31, v154
	s_add_i32 s0, s22, 0xffffe400
	v_lshlrev_b64 v[192:193], 12, v[154:155]
	s_ashr_i32 s1, s0, 31
	v_lshl_add_u64 v[192:193], s[58:59], 0, v[192:193]
	s_mov_b32 s20, 0x437f0000
	s_mov_b32 s21, 0xbfb8aa3b
	v_lshl_add_u64 v[192:193], v[192:193], 0, s[0:1]
	v_lshl_add_u64 v[192:193], v[192:193], 0, v[142:143]
	v_pk_mul_f32 v[172:173], v[126:127], s[20:21] op_sel:[0,1] op_sel_hi:[1,1]
	v_pk_mul_f32 v[174:175], v[128:129], s[20:21] op_sel:[0,1] op_sel_hi:[1,1]
	v_pk_mul_f32 v[176:177], v[122:123], s[20:21] op_sel:[0,1] op_sel_hi:[1,1]
	v_pk_mul_f32 v[178:179], v[124:125], s[20:21] op_sel:[0,1] op_sel_hi:[1,1]
	v_exp_f32_e32 v172, v172
	v_exp_f32_e32 v173, v173
	v_exp_f32_e32 v174, v174
	v_exp_f32_e32 v175, v175
	v_exp_f32_e32 v176, v176
	v_exp_f32_e32 v177, v177
	v_exp_f32_e32 v178, v178
	v_exp_f32_e32 v179, v179
	v_pk_add_f32 v[172:173], v[172:173], 1.0 op_sel_hi:[1,0]
	v_pk_add_f32 v[174:175], v[174:175], 1.0 op_sel_hi:[1,0]
	v_pk_add_f32 v[176:177], v[176:177], 1.0 op_sel_hi:[1,0]
	v_pk_add_f32 v[178:179], v[178:179], 1.0 op_sel_hi:[1,0]
	v_rcp_f32_e32 v172, v172
	v_rcp_f32_e32 v173, v173
	v_rcp_f32_e32 v174, v174
	v_rcp_f32_e32 v175, v175
	v_rcp_f32_e32 v176, v176
	v_rcp_f32_e32 v177, v177
	v_rcp_f32_e32 v178, v178
	v_rcp_f32_e32 v179, v179
	s_nop 0
	v_pk_fma_f32 v[172:173], v[172:173], s[20:21], 0.5 op_sel_hi:[1,0,0]
	v_pk_fma_f32 v[174:175], v[174:175], s[20:21], 0.5 op_sel_hi:[1,0,0]
	v_pk_fma_f32 v[176:177], v[176:177], s[20:21], 0.5 op_sel_hi:[1,0,0]
	v_pk_fma_f32 v[178:179], v[178:179], s[20:21], 0.5 op_sel_hi:[1,0,0]
	v_max_f32_e32 v172, 1.0, v172
	v_max_f32_e32 v173, 1.0, v173
	v_max_f32_e32 v174, 1.0, v174
	v_max_f32_e32 v175, 1.0, v175
	v_max_f32_e32 v176, 1.0, v176
	v_max_f32_e32 v177, 1.0, v177
	v_max_f32_e32 v178, 1.0, v178
	v_max_f32_e32 v179, 1.0, v179
	v_cvt_u32_f32_e32 v180, v172
	v_cvt_u32_f32_e32 v181, v176
	v_cvt_u32_f32_sdwa v180, v173 dst_sel:BYTE_1 dst_unused:UNUSED_PRESERVE src0_sel:DWORD
	v_cvt_u32_f32_sdwa v181, v177 dst_sel:BYTE_1 dst_unused:UNUSED_PRESERVE src0_sel:DWORD
	v_cvt_u32_f32_sdwa v180, v174 dst_sel:BYTE_2 dst_unused:UNUSED_PRESERVE src0_sel:DWORD
	v_cvt_u32_f32_sdwa v181, v178 dst_sel:BYTE_2 dst_unused:UNUSED_PRESERVE src0_sel:DWORD
	v_cvt_u32_f32_sdwa v180, v175 dst_sel:BYTE_3 dst_unused:UNUSED_PRESERVE src0_sel:DWORD
	v_cvt_u32_f32_sdwa v181, v179 dst_sel:BYTE_3 dst_unused:UNUSED_PRESERVE src0_sel:DWORD
	global_store_dwordx2 v[192:193], v[180:181], off
	v_pk_mul_f32 v[182:183], v[118:119], s[20:21] op_sel:[0,1] op_sel_hi:[1,1]
	v_pk_mul_f32 v[184:185], v[120:121], s[20:21] op_sel:[0,1] op_sel_hi:[1,1]
	v_pk_mul_f32 v[186:187], v[110:111], s[20:21] op_sel:[0,1] op_sel_hi:[1,1]
	v_pk_mul_f32 v[188:189], v[112:113], s[20:21] op_sel:[0,1] op_sel_hi:[1,1]
	v_exp_f32_e32 v182, v182
	v_exp_f32_e32 v183, v183
	v_exp_f32_e32 v184, v184
	v_exp_f32_e32 v185, v185
	v_exp_f32_e32 v186, v186
	v_exp_f32_e32 v187, v187
	v_exp_f32_e32 v188, v188
	v_exp_f32_e32 v189, v189
	v_pk_add_f32 v[182:183], v[182:183], 1.0 op_sel_hi:[1,0]
	v_pk_add_f32 v[184:185], v[184:185], 1.0 op_sel_hi:[1,0]
	v_pk_add_f32 v[186:187], v[186:187], 1.0 op_sel_hi:[1,0]
	v_pk_add_f32 v[188:189], v[188:189], 1.0 op_sel_hi:[1,0]
	v_rcp_f32_e32 v182, v182
	v_rcp_f32_e32 v183, v183
	v_rcp_f32_e32 v184, v184
	v_rcp_f32_e32 v185, v185
	v_rcp_f32_e32 v186, v186
	v_rcp_f32_e32 v187, v187
	v_rcp_f32_e32 v188, v188
	v_rcp_f32_e32 v189, v189
	s_nop 0
	v_pk_fma_f32 v[182:183], v[182:183], s[20:21], 0.5 op_sel_hi:[1,0,0]
	v_pk_fma_f32 v[184:185], v[184:185], s[20:21], 0.5 op_sel_hi:[1,0,0]
	v_pk_fma_f32 v[186:187], v[186:187], s[20:21], 0.5 op_sel_hi:[1,0,0]
	v_pk_fma_f32 v[188:189], v[188:189], s[20:21], 0.5 op_sel_hi:[1,0,0]
	v_max_f32_e32 v182, 1.0, v182
	v_max_f32_e32 v183, 1.0, v183
	v_max_f32_e32 v184, 1.0, v184
	v_max_f32_e32 v185, 1.0, v185
	v_max_f32_e32 v186, 1.0, v186
	v_max_f32_e32 v187, 1.0, v187
	v_max_f32_e32 v188, 1.0, v188
	v_max_f32_e32 v189, 1.0, v189
	v_cvt_u32_f32_e32 v190, v182
	v_cvt_u32_f32_e32 v191, v186
	v_cvt_u32_f32_sdwa v190, v183 dst_sel:BYTE_1 dst_unused:UNUSED_PRESERVE src0_sel:DWORD
	v_cvt_u32_f32_sdwa v191, v187 dst_sel:BYTE_1 dst_unused:UNUSED_PRESERVE src0_sel:DWORD
	v_cvt_u32_f32_sdwa v190, v184 dst_sel:BYTE_2 dst_unused:UNUSED_PRESERVE src0_sel:DWORD
	v_cvt_u32_f32_sdwa v191, v188 dst_sel:BYTE_2 dst_unused:UNUSED_PRESERVE src0_sel:DWORD
	v_cvt_u32_f32_sdwa v190, v185 dst_sel:BYTE_3 dst_unused:UNUSED_PRESERVE src0_sel:DWORD
	v_cvt_u32_f32_sdwa v191, v189 dst_sel:BYTE_3 dst_unused:UNUSED_PRESERVE src0_sel:DWORD
	global_store_dwordx2 v[192:193], v[190:191], off offset:128
	v_pk_mul_f32 v[172:173], v[114:115], s[20:21] op_sel:[0,1] op_sel_hi:[1,1]
	v_pk_mul_f32 v[174:175], v[116:117], s[20:21] op_sel:[0,1] op_sel_hi:[1,1]
	v_pk_mul_f32 v[176:177], v[106:107], s[20:21] op_sel:[0,1] op_sel_hi:[1,1]
	v_pk_mul_f32 v[178:179], v[108:109], s[20:21] op_sel:[0,1] op_sel_hi:[1,1]
	v_exp_f32_e32 v172, v172
	v_exp_f32_e32 v173, v173
	v_exp_f32_e32 v174, v174
	v_exp_f32_e32 v175, v175
	v_exp_f32_e32 v176, v176
	v_exp_f32_e32 v177, v177
	v_exp_f32_e32 v178, v178
	v_exp_f32_e32 v179, v179
	v_pk_add_f32 v[172:173], v[172:173], 1.0 op_sel_hi:[1,0]
	v_pk_add_f32 v[174:175], v[174:175], 1.0 op_sel_hi:[1,0]
	v_pk_add_f32 v[176:177], v[176:177], 1.0 op_sel_hi:[1,0]
	v_pk_add_f32 v[178:179], v[178:179], 1.0 op_sel_hi:[1,0]
; __device__ __forceinline__ float sigmoidf_(float x) { return __builtin_amdgcn_rcpf(1.f + __expf(-x)); }
;     __device__ __forceinline__ void operator()(f32x4 (&acc)[2][2][4][2], const pg8::Unit& u, int wr, int wc, int fr, int fq) const {
;     ...
;             for (int ai = 0; ai < 2; ++ai)
; #pragma unroll
;                 for (int m = 0; m < 4; ++m) {
;                     unsigned char* gp = gq + (size_t)(row0 + ai * 128 + m * 16) * 4096 + (u.pn - 28) * 256 + cin;
; #pragma unroll
;                     for (int bj = 0; bj < 2; ++bj) { unsigned w2[2];
; #pragma unroll
;                         for (int n = 0; n < 2; ++n) {
;                             const f32x4 v = acc[ai][bj][m][n];
;                             const unsigned b0 = (unsigned)(sigmoidf_(v[0]) * 255.f + 0.5f), b1 = (unsigned)(sigmoidf_(v[1]) * 255.f + 0.5f),
;                                            b2 = (unsigned)(sigmoidf_(v[2]) * 255.f + 0.5f), b3 = (unsigned)(sigmoidf_(v[3]) * 255.f + 0.5f);
;                             w2[n] = b0 | (b1 << 8) | (b2 << 16) | (b3 << 24);
;                         }
;                         u32x2 o = {w2[0], w2[1]}; *(u32x2*)(gp + bj * 128) = o; }
	v_rcp_f32_e32 v172, v172
	v_rcp_f32_e32 v173, v173
	v_rcp_f32_e32 v174, v174
	v_rcp_f32_e32 v175, v175
	v_rcp_f32_e32 v176, v176
	v_rcp_f32_e32 v177, v177
	v_rcp_f32_e32 v178, v178
	v_rcp_f32_e32 v179, v179
	s_mov_b64 s[0:1], 0x10000
	v_lshl_add_u64 v[196:197], v[192:193], 0, s[0:1]
	v_pk_fma_f32 v[172:173], v[172:173], s[20:21], 0.5 op_sel_hi:[1,0,0]
	v_pk_fma_f32 v[174:175], v[174:175], s[20:21], 0.5 op_sel_hi:[1,0,0]
	v_pk_fma_f32 v[176:177], v[176:177], s[20:21], 0.5 op_sel_hi:[1,0,0]
	v_pk_fma_f32 v[178:179], v[178:179], s[20:21], 0.5 op_sel_hi:[1,0,0]
	v_max_f32_e32 v172, 1.0, v172
	v_max_f32_e32 v173, 1.0, v173
	v_max_f32_e32 v174, 1.0, v174
	v_max_f32_e32 v175, 1.0, v175
	v_max_f32_e32 v176, 1.0, v176
	v_max_f32_e32 v177, 1.0, v177
	v_max_f32_e32 v178, 1.0, v178
	v_max_f32_e32 v179, 1.0, v179
	v_cvt_u32_f32_e32 v180, v172
	v_cvt_u32_f32_e32 v181, v176
	v_cvt_u32_f32_sdwa v180, v173 dst_sel:BYTE_1 dst_unused:UNUSED_PRESERVE src0_sel:DWORD
	v_cvt_u32_f32_sdwa v181, v177 dst_sel:BYTE_1 dst_unused:UNUSED_PRESERVE src0_sel:DWORD
	v_cvt_u32_f32_sdwa v180, v174 dst_sel:BYTE_2 dst_unused:UNUSED_PRESERVE src0_sel:DWORD
	v_cvt_u32_f32_sdwa v181, v178 dst_sel:BYTE_2 dst_unused:UNUSED_PRESERVE src0_sel:DWORD
	v_cvt_u32_f32_sdwa v180, v175 dst_sel:BYTE_3 dst_unused:UNUSED_PRESERVE src0_sel:DWORD
	v_cvt_u32_f32_sdwa v181, v179 dst_sel:BYTE_3 dst_unused:UNUSED_PRESERVE src0_sel:DWORD
	global_store_dwordx2 v[196:197], v[180:181], off
	v_pk_mul_f32 v[182:183], v[98:99], s[20:21] op_sel:[0,1] op_sel_hi:[1,1]
	v_pk_mul_f32 v[184:185], v[100:101], s[20:21] op_sel:[0,1] op_sel_hi:[1,1]
	v_pk_mul_f32 v[186:187], v[90:91], s[20:21] op_sel:[0,1] op_sel_hi:[1,1]
	v_pk_mul_f32 v[188:189], v[92:93], s[20:21] op_sel:[0,1] op_sel_hi:[1,1]
	v_exp_f32_e32 v182, v182
	v_exp_f32_e32 v183, v183
	v_exp_f32_e32 v184, v184
	v_exp_f32_e32 v185, v185
	v_exp_f32_e32 v186, v186
	v_exp_f32_e32 v187, v187
	v_exp_f32_e32 v188, v188
	v_exp_f32_e32 v189, v189
	v_pk_add_f32 v[182:183], v[182:183], 1.0 op_sel_hi:[1,0]
	v_pk_add_f32 v[184:185], v[184:185], 1.0 op_sel_hi:[1,0]
	v_pk_add_f32 v[186:187], v[186:187], 1.0 op_sel_hi:[1,0]
	v_pk_add_f32 v[188:189], v[188:189], 1.0 op_sel_hi:[1,0]
	v_rcp_f32_e32 v182, v182
	v_rcp_f32_e32 v183, v183
	v_rcp_f32_e32 v184, v184
	v_rcp_f32_e32 v185, v185
	v_rcp_f32_e32 v186, v186
	v_rcp_f32_e32 v187, v187
	v_rcp_f32_e32 v188, v188
	v_rcp_f32_e32 v189, v189
	s_nop 0
	v_pk_fma_f32 v[182:183], v[182:183], s[20:21], 0.5 op_sel_hi:[1,0,0]
	v_pk_fma_f32 v[184:185], v[184:185], s[20:21], 0.5 op_sel_hi:[1,0,0]
	v_pk_fma_f32 v[186:187], v[186:187], s[20:21], 0.5 op_sel_hi:[1,0,0]
	v_pk_fma_f32 v[188:189], v[188:189], s[20:21], 0.5 op_sel_hi:[1,0,0]
	v_max_f32_e32 v182, 1.0, v182
	v_max_f32_e32 v183, 1.0, v183
	v_max_f32_e32 v184, 1.0, v184
	v_max_f32_e32 v185, 1.0, v185
	v_max_f32_e32 v186, 1.0, v186
	v_max_f32_e32 v187, 1.0, v187
	v_max_f32_e32 v188, 1.0, v188
	v_max_f32_e32 v189, 1.0, v189
	v_cvt_u32_f32_e32 v190, v182
	v_cvt_u32_f32_e32 v191, v186
	v_cvt_u32_f32_sdwa v190, v183 dst_sel:BYTE_1 dst_unused:UNUSED_PRESERVE src0_sel:DWORD
	v_cvt_u32_f32_sdwa v191, v187 dst_sel:BYTE_1 dst_unused:UNUSED_PRESERVE src0_sel:DWORD
	v_cvt_u32_f32_sdwa v190, v184 dst_sel:BYTE_2 dst_unused:UNUSED_PRESERVE src0_sel:DWORD
	v_cvt_u32_f32_sdwa v191, v188 dst_sel:BYTE_2 dst_unused:UNUSED_PRESERVE src0_sel:DWORD
	v_cvt_u32_f32_sdwa v190, v185 dst_sel:BYTE_3 dst_unused:UNUSED_PRESERVE src0_sel:DWORD
	v_cvt_u32_f32_sdwa v191, v189 dst_sel:BYTE_3 dst_unused:UNUSED_PRESERVE src0_sel:DWORD
	global_store_dwordx2 v[196:197], v[190:191], off offset:128
	v_pk_mul_f32 v[172:173], v[102:103], s[20:21] op_sel:[0,1] op_sel_hi:[1,1]
	v_pk_mul_f32 v[174:175], v[104:105], s[20:21] op_sel:[0,1] op_sel_hi:[1,1]
	v_pk_mul_f32 v[176:177], v[94:95], s[20:21] op_sel:[0,1] op_sel_hi:[1,1]
	v_pk_mul_f32 v[178:179], v[96:97], s[20:21] op_sel:[0,1] op_sel_hi:[1,1]
	v_exp_f32_e32 v172, v172
	v_exp_f32_e32 v173, v173
	v_exp_f32_e32 v174, v174
	v_exp_f32_e32 v175, v175
	v_exp_f32_e32 v176, v176
	v_exp_f32_e32 v177, v177
	v_exp_f32_e32 v178, v178
	v_exp_f32_e32 v179, v179
	v_pk_add_f32 v[172:173], v[172:173], 1.0 op_sel_hi:[1,0]
	v_pk_add_f32 v[174:175], v[174:175], 1.0 op_sel_hi:[1,0]
	v_pk_add_f32 v[176:177], v[176:177], 1.0 op_sel_hi:[1,0]
	v_pk_add_f32 v[178:179], v[178:179], 1.0 op_sel_hi:[1,0]
	v_rcp_f32_e32 v172, v172
	v_rcp_f32_e32 v173, v173
	v_rcp_f32_e32 v174, v174
	v_rcp_f32_e32 v175, v175
	v_rcp_f32_e32 v176, v176
	v_rcp_f32_e32 v177, v177
	v_rcp_f32_e32 v178, v178
	v_rcp_f32_e32 v179, v179
	s_mov_b64 s[0:1], 0x20000
	v_lshl_add_u64 v[194:195], v[192:193], 0, s[0:1]
	v_pk_fma_f32 v[172:173], v[172:173], s[20:21], 0.5 op_sel_hi:[1,0,0]
	v_pk_fma_f32 v[174:175], v[174:175], s[20:21], 0.5 op_sel_hi:[1,0,0]
	v_pk_fma_f32 v[176:177], v[176:177], s[20:21], 0.5 op_sel_hi:[1,0,0]
	v_pk_fma_f32 v[178:179], v[178:179], s[20:21], 0.5 op_sel_hi:[1,0,0]
	v_max_f32_e32 v172, 1.0, v172
	v_max_f32_e32 v173, 1.0, v173
	v_max_f32_e32 v174, 1.0, v174
	v_max_f32_e32 v175, 1.0, v175
	v_max_f32_e32 v176, 1.0, v176
	v_max_f32_e32 v177, 1.0, v177
	v_max_f32_e32 v178, 1.0, v178
	v_max_f32_e32 v179, 1.0, v179
	v_cvt_u32_f32_e32 v180, v172
	v_cvt_u32_f32_e32 v181, v176
	v_cvt_u32_f32_sdwa v180, v173 dst_sel:BYTE_1 dst_unused:UNUSED_PRESERVE src0_sel:DWORD
	v_cvt_u32_f32_sdwa v181, v177 dst_sel:BYTE_1 dst_unused:UNUSED_PRESERVE src0_sel:DWORD
	v_cvt_u32_f32_sdwa v180, v174 dst_sel:BYTE_2 dst_unused:UNUSED_PRESERVE src0_sel:DWORD
	v_cvt_u32_f32_sdwa v181, v178 dst_sel:BYTE_2 dst_unused:UNUSED_PRESERVE src0_sel:DWORD
	v_cvt_u32_f32_sdwa v180, v175 dst_sel:BYTE_3 dst_unused:UNUSED_PRESERVE src0_sel:DWORD
; __device__ __forceinline__ float sigmoidf_(float x) { return __builtin_amdgcn_rcpf(1.f + __expf(-x)); }
;     __device__ __forceinline__ void operator()(f32x4 (&acc)[2][2][4][2], const pg8::Unit& u, int wr, int wc, int fr, int fq) const {
;     ...
;             for (int ai = 0; ai < 2; ++ai)
; #pragma unroll
;                 for (int m = 0; m < 4; ++m) {
;                     unsigned char* gp = gq + (size_t)(row0 + ai * 128 + m * 16) * 4096 + (u.pn - 28) * 256 + cin;
; #pragma unroll
;                     for (int bj = 0; bj < 2; ++bj) { unsigned w2[2];
; #pragma unroll
;                         for (int n = 0; n < 2; ++n) {
;                             const f32x4 v = acc[ai][bj][m][n];
;                             const unsigned b0 = (unsigned)(sigmoidf_(v[0]) * 255.f + 0.5f), b1 = (unsigned)(sigmoidf_(v[1]) * 255.f + 0.5f),
;                                            b2 = (unsigned)(sigmoidf_(v[2]) * 255.f + 0.5f), b3 = (unsigned)(sigmoidf_(v[3]) * 255.f + 0.5f);
;                             w2[n] = b0 | (b1 << 8) | (b2 << 16) | (b3 << 24);
;                         }
;                         u32x2 o = {w2[0], w2[1]}; *(u32x2*)(gp + bj * 128) = o; }
	v_cvt_u32_f32_sdwa v181, v179 dst_sel:BYTE_3 dst_unused:UNUSED_PRESERVE src0_sel:DWORD
	global_store_dwordx2 v[194:195], v[180:181], off
	v_pk_mul_f32 v[182:183], v[82:83], s[20:21] op_sel:[0,1] op_sel_hi:[1,1]
	v_pk_mul_f32 v[184:185], v[84:85], s[20:21] op_sel:[0,1] op_sel_hi:[1,1]
	v_pk_mul_f32 v[186:187], v[74:75], s[20:21] op_sel:[0,1] op_sel_hi:[1,1]
	v_pk_mul_f32 v[188:189], v[76:77], s[20:21] op_sel:[0,1] op_sel_hi:[1,1]
	v_exp_f32_e32 v182, v182
	v_exp_f32_e32 v183, v183
	v_exp_f32_e32 v184, v184
	v_exp_f32_e32 v185, v185
	v_exp_f32_e32 v186, v186
	v_exp_f32_e32 v187, v187
	v_exp_f32_e32 v188, v188
	v_exp_f32_e32 v189, v189
	v_pk_add_f32 v[182:183], v[182:183], 1.0 op_sel_hi:[1,0]
	v_pk_add_f32 v[184:185], v[184:185], 1.0 op_sel_hi:[1,0]
	v_pk_add_f32 v[186:187], v[186:187], 1.0 op_sel_hi:[1,0]
	v_pk_add_f32 v[188:189], v[188:189], 1.0 op_sel_hi:[1,0]
	v_rcp_f32_e32 v182, v182
	v_rcp_f32_e32 v183, v183
	v_rcp_f32_e32 v184, v184
	v_rcp_f32_e32 v185, v185
	v_rcp_f32_e32 v186, v186
	v_rcp_f32_e32 v187, v187
	v_rcp_f32_e32 v188, v188
	v_rcp_f32_e32 v189, v189
	s_nop 0
	v_pk_fma_f32 v[182:183], v[182:183], s[20:21], 0.5 op_sel_hi:[1,0,0]
	v_pk_fma_f32 v[184:185], v[184:185], s[20:21], 0.5 op_sel_hi:[1,0,0]
	v_pk_fma_f32 v[186:187], v[186:187], s[20:21], 0.5 op_sel_hi:[1,0,0]
	v_pk_fma_f32 v[188:189], v[188:189], s[20:21], 0.5 op_sel_hi:[1,0,0]
	v_max_f32_e32 v182, 1.0, v182
	v_max_f32_e32 v183, 1.0, v183
	v_max_f32_e32 v184, 1.0, v184
	v_max_f32_e32 v185, 1.0, v185
	v_max_f32_e32 v186, 1.0, v186
	v_max_f32_e32 v187, 1.0, v187
	v_max_f32_e32 v188, 1.0, v188
	v_max_f32_e32 v189, 1.0, v189
	v_cvt_u32_f32_e32 v190, v182
	v_cvt_u32_f32_e32 v191, v186
	v_cvt_u32_f32_sdwa v190, v183 dst_sel:BYTE_1 dst_unused:UNUSED_PRESERVE src0_sel:DWORD
	v_cvt_u32_f32_sdwa v191, v187 dst_sel:BYTE_1 dst_unused:UNUSED_PRESERVE src0_sel:DWORD
	v_cvt_u32_f32_sdwa v190, v184 dst_sel:BYTE_2 dst_unused:UNUSED_PRESERVE src0_sel:DWORD
	v_cvt_u32_f32_sdwa v191, v188 dst_sel:BYTE_2 dst_unused:UNUSED_PRESERVE src0_sel:DWORD
	v_cvt_u32_f32_sdwa v190, v185 dst_sel:BYTE_3 dst_unused:UNUSED_PRESERVE src0_sel:DWORD
	v_cvt_u32_f32_sdwa v191, v189 dst_sel:BYTE_3 dst_unused:UNUSED_PRESERVE src0_sel:DWORD
	global_store_dwordx2 v[194:195], v[190:191], off offset:128
	v_pk_mul_f32 v[172:173], v[86:87], s[20:21] op_sel:[0,1] op_sel_hi:[1,1]
	v_pk_mul_f32 v[174:175], v[88:89], s[20:21] op_sel:[0,1] op_sel_hi:[1,1]
	v_pk_mul_f32 v[176:177], v[78:79], s[20:21] op_sel:[0,1] op_sel_hi:[1,1]
	v_pk_mul_f32 v[178:179], v[80:81], s[20:21] op_sel:[0,1] op_sel_hi:[1,1]
	v_exp_f32_e32 v172, v172
	v_exp_f32_e32 v173, v173
	v_exp_f32_e32 v174, v174
	v_exp_f32_e32 v175, v175
	v_exp_f32_e32 v176, v176
	v_exp_f32_e32 v177, v177
	v_exp_f32_e32 v178, v178
	v_exp_f32_e32 v179, v179
	v_pk_add_f32 v[172:173], v[172:173], 1.0 op_sel_hi:[1,0]
	v_pk_add_f32 v[174:175], v[174:175], 1.0 op_sel_hi:[1,0]
	v_pk_add_f32 v[176:177], v[176:177], 1.0 op_sel_hi:[1,0]
	v_pk_add_f32 v[178:179], v[178:179], 1.0 op_sel_hi:[1,0]
	v_rcp_f32_e32 v172, v172
	v_rcp_f32_e32 v173, v173
	v_rcp_f32_e32 v174, v174
	v_rcp_f32_e32 v175, v175
	v_rcp_f32_e32 v176, v176
	v_rcp_f32_e32 v177, v177
	v_rcp_f32_e32 v178, v178
	v_rcp_f32_e32 v179, v179
	s_mov_b64 s[0:1], 0x30000
	v_lshl_add_u64 v[196:197], v[192:193], 0, s[0:1]
	v_pk_fma_f32 v[172:173], v[172:173], s[20:21], 0.5 op_sel_hi:[1,0,0]
	v_pk_fma_f32 v[174:175], v[174:175], s[20:21], 0.5 op_sel_hi:[1,0,0]
	v_pk_fma_f32 v[176:177], v[176:177], s[20:21], 0.5 op_sel_hi:[1,0,0]
	v_pk_fma_f32 v[178:179], v[178:179], s[20:21], 0.5 op_sel_hi:[1,0,0]
	v_max_f32_e32 v172, 1.0, v172
	v_max_f32_e32 v173, 1.0, v173
	v_max_f32_e32 v174, 1.0, v174
	v_max_f32_e32 v175, 1.0, v175
	v_max_f32_e32 v176, 1.0, v176
	v_max_f32_e32 v177, 1.0, v177
	v_max_f32_e32 v178, 1.0, v178
	v_max_f32_e32 v179, 1.0, v179
	v_cvt_u32_f32_e32 v180, v172
	v_cvt_u32_f32_e32 v181, v176
	v_cvt_u32_f32_sdwa v180, v173 dst_sel:BYTE_1 dst_unused:UNUSED_PRESERVE src0_sel:DWORD
	v_cvt_u32_f32_sdwa v181, v177 dst_sel:BYTE_1 dst_unused:UNUSED_PRESERVE src0_sel:DWORD
	v_cvt_u32_f32_sdwa v180, v174 dst_sel:BYTE_2 dst_unused:UNUSED_PRESERVE src0_sel:DWORD
	v_cvt_u32_f32_sdwa v181, v178 dst_sel:BYTE_2 dst_unused:UNUSED_PRESERVE src0_sel:DWORD
	v_cvt_u32_f32_sdwa v180, v175 dst_sel:BYTE_3 dst_unused:UNUSED_PRESERVE src0_sel:DWORD
	v_cvt_u32_f32_sdwa v181, v179 dst_sel:BYTE_3 dst_unused:UNUSED_PRESERVE src0_sel:DWORD
	global_store_dwordx2 v[196:197], v[180:181], off
	v_pk_mul_f32 v[182:183], v[70:71], s[20:21] op_sel:[0,1] op_sel_hi:[1,1]
	v_pk_mul_f32 v[184:185], v[72:73], s[20:21] op_sel:[0,1] op_sel_hi:[1,1]
	v_pk_mul_f32 v[186:187], v[66:67], s[20:21] op_sel:[0,1] op_sel_hi:[1,1]
	v_pk_mul_f32 v[188:189], v[68:69], s[20:21] op_sel:[0,1] op_sel_hi:[1,1]
	v_exp_f32_e32 v182, v182
	v_exp_f32_e32 v183, v183
	v_exp_f32_e32 v184, v184
	v_exp_f32_e32 v185, v185
	v_exp_f32_e32 v186, v186
	v_exp_f32_e32 v187, v187
	v_exp_f32_e32 v188, v188
	v_exp_f32_e32 v189, v189
	v_pk_add_f32 v[182:183], v[182:183], 1.0 op_sel_hi:[1,0]
	v_pk_add_f32 v[184:185], v[184:185], 1.0 op_sel_hi:[1,0]
	v_pk_add_f32 v[186:187], v[186:187], 1.0 op_sel_hi:[1,0]
	v_pk_add_f32 v[188:189], v[188:189], 1.0 op_sel_hi:[1,0]
	v_rcp_f32_e32 v182, v182
	v_rcp_f32_e32 v183, v183
	v_rcp_f32_e32 v184, v184
	v_rcp_f32_e32 v185, v185
	v_rcp_f32_e32 v186, v186
	v_rcp_f32_e32 v187, v187
	v_rcp_f32_e32 v188, v188
	v_rcp_f32_e32 v189, v189
	s_nop 0
	v_pk_fma_f32 v[182:183], v[182:183], s[20:21], 0.5 op_sel_hi:[1,0,0]
	v_pk_fma_f32 v[184:185], v[184:185], s[20:21], 0.5 op_sel_hi:[1,0,0]
	v_pk_fma_f32 v[186:187], v[186:187], s[20:21], 0.5 op_sel_hi:[1,0,0]
; __device__ __forceinline__ float sigmoidf_(float x) { return __builtin_amdgcn_rcpf(1.f + __expf(-x)); }
;     __device__ __forceinline__ void operator()(f32x4 (&acc)[2][2][4][2], const pg8::Unit& u, int wr, int wc, int fr, int fq) const {
;     ...
;             for (int ai = 0; ai < 2; ++ai)
; #pragma unroll
;                 for (int m = 0; m < 4; ++m) {
;                     unsigned char* gp = gq + (size_t)(row0 + ai * 128 + m * 16) * 4096 + (u.pn - 28) * 256 + cin;
; #pragma unroll
;                     for (int bj = 0; bj < 2; ++bj) { unsigned w2[2];
; #pragma unroll
;                         for (int n = 0; n < 2; ++n) {
;                             const f32x4 v = acc[ai][bj][m][n];
;                             const unsigned b0 = (unsigned)(sigmoidf_(v[0]) * 255.f + 0.5f), b1 = (unsigned)(sigmoidf_(v[1]) * 255.f + 0.5f),
;                                            b2 = (unsigned)(sigmoidf_(v[2]) * 255.f + 0.5f), b3 = (unsigned)(sigmoidf_(v[3]) * 255.f + 0.5f);
;                             w2[n] = b0 | (b1 << 8) | (b2 << 16) | (b3 << 24);
;                         }
;                         u32x2 o = {w2[0], w2[1]}; *(u32x2*)(gp + bj * 128) = o; }
	v_pk_fma_f32 v[188:189], v[188:189], s[20:21], 0.5 op_sel_hi:[1,0,0]
	v_max_f32_e32 v182, 1.0, v182
	v_max_f32_e32 v183, 1.0, v183
	v_max_f32_e32 v184, 1.0, v184
	v_max_f32_e32 v185, 1.0, v185
	v_max_f32_e32 v186, 1.0, v186
	v_max_f32_e32 v187, 1.0, v187
	v_max_f32_e32 v188, 1.0, v188
	v_max_f32_e32 v189, 1.0, v189
	v_cvt_u32_f32_e32 v190, v182
	v_cvt_u32_f32_e32 v191, v186
	v_cvt_u32_f32_sdwa v190, v183 dst_sel:BYTE_1 dst_unused:UNUSED_PRESERVE src0_sel:DWORD
	v_cvt_u32_f32_sdwa v191, v187 dst_sel:BYTE_1 dst_unused:UNUSED_PRESERVE src0_sel:DWORD
	v_cvt_u32_f32_sdwa v190, v184 dst_sel:BYTE_2 dst_unused:UNUSED_PRESERVE src0_sel:DWORD
	v_cvt_u32_f32_sdwa v191, v188 dst_sel:BYTE_2 dst_unused:UNUSED_PRESERVE src0_sel:DWORD
	v_cvt_u32_f32_sdwa v190, v185 dst_sel:BYTE_3 dst_unused:UNUSED_PRESERVE src0_sel:DWORD
	v_cvt_u32_f32_sdwa v191, v189 dst_sel:BYTE_3 dst_unused:UNUSED_PRESERVE src0_sel:DWORD
	global_store_dwordx2 v[196:197], v[190:191], off offset:128
	v_pk_mul_f32 v[172:173], v[62:63], s[20:21] op_sel:[0,1] op_sel_hi:[1,1]
	v_pk_mul_f32 v[174:175], v[64:65], s[20:21] op_sel:[0,1] op_sel_hi:[1,1]
	v_pk_mul_f32 v[176:177], v[58:59], s[20:21] op_sel:[0,1] op_sel_hi:[1,1]
	v_pk_mul_f32 v[178:179], v[60:61], s[20:21] op_sel:[0,1] op_sel_hi:[1,1]
	v_exp_f32_e32 v172, v172
	v_exp_f32_e32 v173, v173
	v_exp_f32_e32 v174, v174
	v_exp_f32_e32 v175, v175
	v_exp_f32_e32 v176, v176
	v_exp_f32_e32 v177, v177
	v_exp_f32_e32 v178, v178
	v_exp_f32_e32 v179, v179
	v_pk_add_f32 v[172:173], v[172:173], 1.0 op_sel_hi:[1,0]
	v_pk_add_f32 v[174:175], v[174:175], 1.0 op_sel_hi:[1,0]
	v_pk_add_f32 v[176:177], v[176:177], 1.0 op_sel_hi:[1,0]
	v_pk_add_f32 v[178:179], v[178:179], 1.0 op_sel_hi:[1,0]
	v_rcp_f32_e32 v172, v172
	v_rcp_f32_e32 v173, v173
	v_rcp_f32_e32 v174, v174
	v_rcp_f32_e32 v175, v175
	v_rcp_f32_e32 v176, v176
	v_rcp_f32_e32 v177, v177
	v_rcp_f32_e32 v178, v178
	v_rcp_f32_e32 v179, v179
	s_mov_b64 s[0:1], 0x80000
	v_lshl_add_u64 v[194:195], v[192:193], 0, s[0:1]
	v_pk_fma_f32 v[172:173], v[172:173], s[20:21], 0.5 op_sel_hi:[1,0,0]
	v_pk_fma_f32 v[174:175], v[174:175], s[20:21], 0.5 op_sel_hi:[1,0,0]
	v_pk_fma_f32 v[176:177], v[176:177], s[20:21], 0.5 op_sel_hi:[1,0,0]
	v_pk_fma_f32 v[178:179], v[178:179], s[20:21], 0.5 op_sel_hi:[1,0,0]
	v_max_f32_e32 v172, 1.0, v172
	v_max_f32_e32 v173, 1.0, v173
	v_max_f32_e32 v174, 1.0, v174
	v_max_f32_e32 v175, 1.0, v175
	v_max_f32_e32 v176, 1.0, v176
	v_max_f32_e32 v177, 1.0, v177
	v_max_f32_e32 v178, 1.0, v178
	v_max_f32_e32 v179, 1.0, v179
	v_cvt_u32_f32_e32 v180, v172
	v_cvt_u32_f32_e32 v181, v176
	v_cvt_u32_f32_sdwa v180, v173 dst_sel:BYTE_1 dst_unused:UNUSED_PRESERVE src0_sel:DWORD
	v_cvt_u32_f32_sdwa v181, v177 dst_sel:BYTE_1 dst_unused:UNUSED_PRESERVE src0_sel:DWORD
	v_cvt_u32_f32_sdwa v180, v174 dst_sel:BYTE_2 dst_unused:UNUSED_PRESERVE src0_sel:DWORD
	v_cvt_u32_f32_sdwa v181, v178 dst_sel:BYTE_2 dst_unused:UNUSED_PRESERVE src0_sel:DWORD
	v_cvt_u32_f32_sdwa v180, v175 dst_sel:BYTE_3 dst_unused:UNUSED_PRESERVE src0_sel:DWORD
	v_cvt_u32_f32_sdwa v181, v179 dst_sel:BYTE_3 dst_unused:UNUSED_PRESERVE src0_sel:DWORD
	global_store_dwordx2 v[194:195], v[180:181], off
	v_pk_mul_f32 v[182:183], v[54:55], s[20:21] op_sel:[0,1] op_sel_hi:[1,1]
	v_pk_mul_f32 v[184:185], v[56:57], s[20:21] op_sel:[0,1] op_sel_hi:[1,1]
	v_pk_mul_f32 v[186:187], v[46:47], s[20:21] op_sel:[0,1] op_sel_hi:[1,1]
	v_pk_mul_f32 v[188:189], v[48:49], s[20:21] op_sel:[0,1] op_sel_hi:[1,1]
	v_exp_f32_e32 v182, v182
	v_exp_f32_e32 v183, v183
	v_exp_f32_e32 v184, v184
	v_exp_f32_e32 v185, v185
	v_exp_f32_e32 v186, v186
	v_exp_f32_e32 v187, v187
	v_exp_f32_e32 v188, v188
	v_exp_f32_e32 v189, v189
	v_pk_add_f32 v[182:183], v[182:183], 1.0 op_sel_hi:[1,0]
	v_pk_add_f32 v[184:185], v[184:185], 1.0 op_sel_hi:[1,0]
	v_pk_add_f32 v[186:187], v[186:187], 1.0 op_sel_hi:[1,0]
	v_pk_add_f32 v[188:189], v[188:189], 1.0 op_sel_hi:[1,0]
	v_rcp_f32_e32 v182, v182
	v_rcp_f32_e32 v183, v183
	v_rcp_f32_e32 v184, v184
	v_rcp_f32_e32 v185, v185
	v_rcp_f32_e32 v186, v186
	v_rcp_f32_e32 v187, v187
	v_rcp_f32_e32 v188, v188
	v_rcp_f32_e32 v189, v189
	s_nop 0
	v_pk_fma_f32 v[182:183], v[182:183], s[20:21], 0.5 op_sel_hi:[1,0,0]
	v_pk_fma_f32 v[184:185], v[184:185], s[20:21], 0.5 op_sel_hi:[1,0,0]
	v_pk_fma_f32 v[186:187], v[186:187], s[20:21], 0.5 op_sel_hi:[1,0,0]
	v_pk_fma_f32 v[188:189], v[188:189], s[20:21], 0.5 op_sel_hi:[1,0,0]
	v_max_f32_e32 v182, 1.0, v182
	v_max_f32_e32 v183, 1.0, v183
	v_max_f32_e32 v184, 1.0, v184
	v_max_f32_e32 v185, 1.0, v185
	v_max_f32_e32 v186, 1.0, v186
	v_max_f32_e32 v187, 1.0, v187
	v_max_f32_e32 v188, 1.0, v188
	v_max_f32_e32 v189, 1.0, v189
	v_cvt_u32_f32_e32 v190, v182
	v_cvt_u32_f32_e32 v191, v186
	v_cvt_u32_f32_sdwa v190, v183 dst_sel:BYTE_1 dst_unused:UNUSED_PRESERVE src0_sel:DWORD
	v_cvt_u32_f32_sdwa v191, v187 dst_sel:BYTE_1 dst_unused:UNUSED_PRESERVE src0_sel:DWORD
	v_cvt_u32_f32_sdwa v190, v184 dst_sel:BYTE_2 dst_unused:UNUSED_PRESERVE src0_sel:DWORD
	v_cvt_u32_f32_sdwa v191, v188 dst_sel:BYTE_2 dst_unused:UNUSED_PRESERVE src0_sel:DWORD
	v_cvt_u32_f32_sdwa v190, v185 dst_sel:BYTE_3 dst_unused:UNUSED_PRESERVE src0_sel:DWORD
	v_cvt_u32_f32_sdwa v191, v189 dst_sel:BYTE_3 dst_unused:UNUSED_PRESERVE src0_sel:DWORD
	global_store_dwordx2 v[194:195], v[190:191], off offset:128
	v_pk_mul_f32 v[172:173], v[50:51], s[20:21] op_sel:[0,1] op_sel_hi:[1,1]
	v_pk_mul_f32 v[174:175], v[52:53], s[20:21] op_sel:[0,1] op_sel_hi:[1,1]
	v_pk_mul_f32 v[176:177], v[42:43], s[20:21] op_sel:[0,1] op_sel_hi:[1,1]
	v_pk_mul_f32 v[178:179], v[44:45], s[20:21] op_sel:[0,1] op_sel_hi:[1,1]
	v_exp_f32_e32 v172, v172
	v_exp_f32_e32 v173, v173
; __device__ __forceinline__ float sigmoidf_(float x) { return __builtin_amdgcn_rcpf(1.f + __expf(-x)); }
;     __device__ __forceinline__ void operator()(f32x4 (&acc)[2][2][4][2], const pg8::Unit& u, int wr, int wc, int fr, int fq) const {
;     ...
;             for (int ai = 0; ai < 2; ++ai)
; #pragma unroll
;                 for (int m = 0; m < 4; ++m) {
;                     unsigned char* gp = gq + (size_t)(row0 + ai * 128 + m * 16) * 4096 + (u.pn - 28) * 256 + cin;
; #pragma unroll
;                     for (int bj = 0; bj < 2; ++bj) { unsigned w2[2];
; #pragma unroll
;                         for (int n = 0; n < 2; ++n) {
;                             const f32x4 v = acc[ai][bj][m][n];
;                             const unsigned b0 = (unsigned)(sigmoidf_(v[0]) * 255.f + 0.5f), b1 = (unsigned)(sigmoidf_(v[1]) * 255.f + 0.5f),
;                                            b2 = (unsigned)(sigmoidf_(v[2]) * 255.f + 0.5f), b3 = (unsigned)(sigmoidf_(v[3]) * 255.f + 0.5f);
;                             w2[n] = b0 | (b1 << 8) | (b2 << 16) | (b3 << 24);
;                         }
;                         u32x2 o = {w2[0], w2[1]}; *(u32x2*)(gp + bj * 128) = o; }
	v_exp_f32_e32 v174, v174
	v_exp_f32_e32 v175, v175
	v_exp_f32_e32 v176, v176
	v_exp_f32_e32 v177, v177
	v_exp_f32_e32 v178, v178
	v_exp_f32_e32 v179, v179
	v_pk_add_f32 v[172:173], v[172:173], 1.0 op_sel_hi:[1,0]
	v_pk_add_f32 v[174:175], v[174:175], 1.0 op_sel_hi:[1,0]
	v_pk_add_f32 v[176:177], v[176:177], 1.0 op_sel_hi:[1,0]
	v_pk_add_f32 v[178:179], v[178:179], 1.0 op_sel_hi:[1,0]
	v_rcp_f32_e32 v172, v172
	v_rcp_f32_e32 v173, v173
	v_rcp_f32_e32 v174, v174
	v_rcp_f32_e32 v175, v175
	v_rcp_f32_e32 v176, v176
	v_rcp_f32_e32 v177, v177
	v_rcp_f32_e32 v178, v178
	v_rcp_f32_e32 v179, v179
	s_mov_b64 s[0:1], 0x90000
	v_lshl_add_u64 v[196:197], v[192:193], 0, s[0:1]
	v_pk_fma_f32 v[172:173], v[172:173], s[20:21], 0.5 op_sel_hi:[1,0,0]
	v_pk_fma_f32 v[174:175], v[174:175], s[20:21], 0.5 op_sel_hi:[1,0,0]
	v_pk_fma_f32 v[176:177], v[176:177], s[20:21], 0.5 op_sel_hi:[1,0,0]
	v_pk_fma_f32 v[178:179], v[178:179], s[20:21], 0.5 op_sel_hi:[1,0,0]
	v_max_f32_e32 v172, 1.0, v172
	v_max_f32_e32 v173, 1.0, v173
	v_max_f32_e32 v174, 1.0, v174
	v_max_f32_e32 v175, 1.0, v175
	v_max_f32_e32 v176, 1.0, v176
	v_max_f32_e32 v177, 1.0, v177
	v_max_f32_e32 v178, 1.0, v178
	v_max_f32_e32 v179, 1.0, v179
	v_cvt_u32_f32_e32 v180, v172
	v_cvt_u32_f32_e32 v181, v176
	v_cvt_u32_f32_sdwa v180, v173 dst_sel:BYTE_1 dst_unused:UNUSED_PRESERVE src0_sel:DWORD
	v_cvt_u32_f32_sdwa v181, v177 dst_sel:BYTE_1 dst_unused:UNUSED_PRESERVE src0_sel:DWORD
	v_cvt_u32_f32_sdwa v180, v174 dst_sel:BYTE_2 dst_unused:UNUSED_PRESERVE src0_sel:DWORD
	v_cvt_u32_f32_sdwa v181, v178 dst_sel:BYTE_2 dst_unused:UNUSED_PRESERVE src0_sel:DWORD
	v_cvt_u32_f32_sdwa v180, v175 dst_sel:BYTE_3 dst_unused:UNUSED_PRESERVE src0_sel:DWORD
	v_cvt_u32_f32_sdwa v181, v179 dst_sel:BYTE_3 dst_unused:UNUSED_PRESERVE src0_sel:DWORD
	global_store_dwordx2 v[196:197], v[180:181], off
	v_pk_mul_f32 v[182:183], v[34:35], s[20:21] op_sel:[0,1] op_sel_hi:[1,1]
	v_pk_mul_f32 v[184:185], v[36:37], s[20:21] op_sel:[0,1] op_sel_hi:[1,1]
	v_pk_mul_f32 v[186:187], v[26:27], s[20:21] op_sel:[0,1] op_sel_hi:[1,1]
	v_pk_mul_f32 v[188:189], v[28:29], s[20:21] op_sel:[0,1] op_sel_hi:[1,1]
	v_exp_f32_e32 v182, v182
	v_exp_f32_e32 v183, v183
	v_exp_f32_e32 v184, v184
	v_exp_f32_e32 v185, v185
	v_exp_f32_e32 v186, v186
	v_exp_f32_e32 v187, v187
	v_exp_f32_e32 v188, v188
	v_exp_f32_e32 v189, v189
	v_pk_add_f32 v[182:183], v[182:183], 1.0 op_sel_hi:[1,0]
	v_pk_add_f32 v[184:185], v[184:185], 1.0 op_sel_hi:[1,0]
	v_pk_add_f32 v[186:187], v[186:187], 1.0 op_sel_hi:[1,0]
	v_pk_add_f32 v[188:189], v[188:189], 1.0 op_sel_hi:[1,0]
	v_rcp_f32_e32 v182, v182
	v_rcp_f32_e32 v183, v183
	v_rcp_f32_e32 v184, v184
	v_rcp_f32_e32 v185, v185
	v_rcp_f32_e32 v186, v186
	v_rcp_f32_e32 v187, v187
	v_rcp_f32_e32 v188, v188
	v_rcp_f32_e32 v189, v189
	s_nop 0
	v_pk_fma_f32 v[182:183], v[182:183], s[20:21], 0.5 op_sel_hi:[1,0,0]
	v_pk_fma_f32 v[184:185], v[184:185], s[20:21], 0.5 op_sel_hi:[1,0,0]
	v_pk_fma_f32 v[186:187], v[186:187], s[20:21], 0.5 op_sel_hi:[1,0,0]
	v_pk_fma_f32 v[188:189], v[188:189], s[20:21], 0.5 op_sel_hi:[1,0,0]
	v_max_f32_e32 v182, 1.0, v182
	v_max_f32_e32 v183, 1.0, v183
	v_max_f32_e32 v184, 1.0, v184
	v_max_f32_e32 v185, 1.0, v185
	v_max_f32_e32 v186, 1.0, v186
	v_max_f32_e32 v187, 1.0, v187
	v_max_f32_e32 v188, 1.0, v188
	v_max_f32_e32 v189, 1.0, v189
	v_cvt_u32_f32_e32 v190, v182
	v_cvt_u32_f32_e32 v191, v186
	v_cvt_u32_f32_sdwa v190, v183 dst_sel:BYTE_1 dst_unused:UNUSED_PRESERVE src0_sel:DWORD
	v_cvt_u32_f32_sdwa v191, v187 dst_sel:BYTE_1 dst_unused:UNUSED_PRESERVE src0_sel:DWORD
	v_cvt_u32_f32_sdwa v190, v184 dst_sel:BYTE_2 dst_unused:UNUSED_PRESERVE src0_sel:DWORD
	v_cvt_u32_f32_sdwa v191, v188 dst_sel:BYTE_2 dst_unused:UNUSED_PRESERVE src0_sel:DWORD
	v_cvt_u32_f32_sdwa v190, v185 dst_sel:BYTE_3 dst_unused:UNUSED_PRESERVE src0_sel:DWORD
	v_cvt_u32_f32_sdwa v191, v189 dst_sel:BYTE_3 dst_unused:UNUSED_PRESERVE src0_sel:DWORD
	global_store_dwordx2 v[196:197], v[190:191], off offset:128
	v_pk_mul_f32 v[172:173], v[38:39], s[20:21] op_sel:[0,1] op_sel_hi:[1,1]
	v_pk_mul_f32 v[174:175], v[40:41], s[20:21] op_sel:[0,1] op_sel_hi:[1,1]
	v_pk_mul_f32 v[176:177], v[30:31], s[20:21] op_sel:[0,1] op_sel_hi:[1,1]
	v_pk_mul_f32 v[178:179], v[32:33], s[20:21] op_sel:[0,1] op_sel_hi:[1,1]
	v_exp_f32_e32 v172, v172
	v_exp_f32_e32 v173, v173
	v_exp_f32_e32 v174, v174
	v_exp_f32_e32 v175, v175
	v_exp_f32_e32 v176, v176
	v_exp_f32_e32 v177, v177
	v_exp_f32_e32 v178, v178
	v_exp_f32_e32 v179, v179
	v_pk_add_f32 v[172:173], v[172:173], 1.0 op_sel_hi:[1,0]
	v_pk_add_f32 v[174:175], v[174:175], 1.0 op_sel_hi:[1,0]
	v_pk_add_f32 v[176:177], v[176:177], 1.0 op_sel_hi:[1,0]
	v_pk_add_f32 v[178:179], v[178:179], 1.0 op_sel_hi:[1,0]
	v_rcp_f32_e32 v172, v172
	v_rcp_f32_e32 v173, v173
	v_rcp_f32_e32 v174, v174
	v_rcp_f32_e32 v175, v175
	v_rcp_f32_e32 v176, v176
	v_rcp_f32_e32 v177, v177
	v_rcp_f32_e32 v178, v178
	v_rcp_f32_e32 v179, v179
	s_mov_b64 s[0:1], 0xa0000
	v_lshl_add_u64 v[194:195], v[192:193], 0, s[0:1]
	v_pk_fma_f32 v[172:173], v[172:173], s[20:21], 0.5 op_sel_hi:[1,0,0]
	v_pk_fma_f32 v[174:175], v[174:175], s[20:21], 0.5 op_sel_hi:[1,0,0]
	v_pk_fma_f32 v[176:177], v[176:177], s[20:21], 0.5 op_sel_hi:[1,0,0]
	v_pk_fma_f32 v[178:179], v[178:179], s[20:21], 0.5 op_sel_hi:[1,0,0]
	v_max_f32_e32 v172, 1.0, v172
	v_max_f32_e32 v173, 1.0, v173
	v_max_f32_e32 v174, 1.0, v174
	v_max_f32_e32 v175, 1.0, v175
	v_max_f32_e32 v176, 1.0, v176
	v_max_f32_e32 v177, 1.0, v177
	v_max_f32_e32 v178, 1.0, v178
	v_max_f32_e32 v179, 1.0, v179
	v_cvt_u32_f32_e32 v180, v172
	v_cvt_u32_f32_e32 v181, v176
	v_cvt_u32_f32_sdwa v180, v173 dst_sel:BYTE_1 dst_unused:UNUSED_PRESERVE src0_sel:DWORD
; __device__ __forceinline__ float sigmoidf_(float x) { return __builtin_amdgcn_rcpf(1.f + __expf(-x)); }
;     __device__ __forceinline__ void operator()(f32x4 (&acc)[2][2][4][2], const pg8::Unit& u, int wr, int wc, int fr, int fq) const {
;     ...
;             for (int ai = 0; ai < 2; ++ai)
; #pragma unroll
;                 for (int m = 0; m < 4; ++m) {
;                     unsigned char* gp = gq + (size_t)(row0 + ai * 128 + m * 16) * 4096 + (u.pn - 28) * 256 + cin;
; #pragma unroll
;                     for (int bj = 0; bj < 2; ++bj) { unsigned w2[2];
; #pragma unroll
;                         for (int n = 0; n < 2; ++n) {
;                             const f32x4 v = acc[ai][bj][m][n];
;                             const unsigned b0 = (unsigned)(sigmoidf_(v[0]) * 255.f + 0.5f), b1 = (unsigned)(sigmoidf_(v[1]) * 255.f + 0.5f),
;                                            b2 = (unsigned)(sigmoidf_(v[2]) * 255.f + 0.5f), b3 = (unsigned)(sigmoidf_(v[3]) * 255.f + 0.5f);
;                             w2[n] = b0 | (b1 << 8) | (b2 << 16) | (b3 << 24);
;                         }
;                         u32x2 o = {w2[0], w2[1]}; *(u32x2*)(gp + bj * 128) = o; }
	v_cvt_u32_f32_sdwa v181, v177 dst_sel:BYTE_1 dst_unused:UNUSED_PRESERVE src0_sel:DWORD
	v_cvt_u32_f32_sdwa v180, v174 dst_sel:BYTE_2 dst_unused:UNUSED_PRESERVE src0_sel:DWORD
	v_cvt_u32_f32_sdwa v181, v178 dst_sel:BYTE_2 dst_unused:UNUSED_PRESERVE src0_sel:DWORD
	v_cvt_u32_f32_sdwa v180, v175 dst_sel:BYTE_3 dst_unused:UNUSED_PRESERVE src0_sel:DWORD
	v_cvt_u32_f32_sdwa v181, v179 dst_sel:BYTE_3 dst_unused:UNUSED_PRESERVE src0_sel:DWORD
	global_store_dwordx2 v[194:195], v[180:181], off
	v_pk_mul_f32 v[182:183], v[18:19], s[20:21] op_sel:[0,1] op_sel_hi:[1,1]
	v_pk_mul_f32 v[184:185], v[20:21], s[20:21] op_sel:[0,1] op_sel_hi:[1,1]
	v_pk_mul_f32 v[186:187], v[10:11], s[20:21] op_sel:[0,1] op_sel_hi:[1,1]
	v_pk_mul_f32 v[188:189], v[12:13], s[20:21] op_sel:[0,1] op_sel_hi:[1,1]
	v_exp_f32_e32 v182, v182
	v_exp_f32_e32 v183, v183
	v_exp_f32_e32 v184, v184
	v_exp_f32_e32 v185, v185
	v_exp_f32_e32 v186, v186
	v_exp_f32_e32 v187, v187
	v_exp_f32_e32 v188, v188
	v_exp_f32_e32 v189, v189
	v_pk_add_f32 v[182:183], v[182:183], 1.0 op_sel_hi:[1,0]
	v_pk_add_f32 v[184:185], v[184:185], 1.0 op_sel_hi:[1,0]
	v_pk_add_f32 v[186:187], v[186:187], 1.0 op_sel_hi:[1,0]
	v_pk_add_f32 v[188:189], v[188:189], 1.0 op_sel_hi:[1,0]
	v_rcp_f32_e32 v182, v182
	v_rcp_f32_e32 v183, v183
	v_rcp_f32_e32 v184, v184
	v_rcp_f32_e32 v185, v185
	v_rcp_f32_e32 v186, v186
	v_rcp_f32_e32 v187, v187
	v_rcp_f32_e32 v188, v188
	v_rcp_f32_e32 v189, v189
	s_nop 0
	v_pk_fma_f32 v[182:183], v[182:183], s[20:21], 0.5 op_sel_hi:[1,0,0]
	v_pk_fma_f32 v[184:185], v[184:185], s[20:21], 0.5 op_sel_hi:[1,0,0]
	v_pk_fma_f32 v[186:187], v[186:187], s[20:21], 0.5 op_sel_hi:[1,0,0]
	v_pk_fma_f32 v[188:189], v[188:189], s[20:21], 0.5 op_sel_hi:[1,0,0]
	v_max_f32_e32 v182, 1.0, v182
	v_max_f32_e32 v183, 1.0, v183
	v_max_f32_e32 v184, 1.0, v184
	v_max_f32_e32 v185, 1.0, v185
	v_max_f32_e32 v186, 1.0, v186
	v_max_f32_e32 v187, 1.0, v187
	v_max_f32_e32 v188, 1.0, v188
	v_max_f32_e32 v189, 1.0, v189
	v_cvt_u32_f32_e32 v190, v182
	v_cvt_u32_f32_e32 v191, v186
	v_cvt_u32_f32_sdwa v190, v183 dst_sel:BYTE_1 dst_unused:UNUSED_PRESERVE src0_sel:DWORD
	v_cvt_u32_f32_sdwa v191, v187 dst_sel:BYTE_1 dst_unused:UNUSED_PRESERVE src0_sel:DWORD
	v_cvt_u32_f32_sdwa v190, v184 dst_sel:BYTE_2 dst_unused:UNUSED_PRESERVE src0_sel:DWORD
	v_cvt_u32_f32_sdwa v191, v188 dst_sel:BYTE_2 dst_unused:UNUSED_PRESERVE src0_sel:DWORD
	v_cvt_u32_f32_sdwa v190, v185 dst_sel:BYTE_3 dst_unused:UNUSED_PRESERVE src0_sel:DWORD
	v_cvt_u32_f32_sdwa v191, v189 dst_sel:BYTE_3 dst_unused:UNUSED_PRESERVE src0_sel:DWORD
	global_store_dwordx2 v[194:195], v[190:191], off offset:128
	v_pk_mul_f32 v[172:173], v[22:23], s[20:21] op_sel:[0,1] op_sel_hi:[1,1]
	v_pk_mul_f32 v[174:175], v[24:25], s[20:21] op_sel:[0,1] op_sel_hi:[1,1]
	v_pk_mul_f32 v[176:177], v[14:15], s[20:21] op_sel:[0,1] op_sel_hi:[1,1]
	v_pk_mul_f32 v[178:179], v[16:17], s[20:21] op_sel:[0,1] op_sel_hi:[1,1]
	v_exp_f32_e32 v172, v172
	v_exp_f32_e32 v173, v173
	v_exp_f32_e32 v174, v174
	v_exp_f32_e32 v175, v175
	v_exp_f32_e32 v176, v176
	v_exp_f32_e32 v177, v177
	v_exp_f32_e32 v178, v178
	v_exp_f32_e32 v179, v179
	v_pk_add_f32 v[172:173], v[172:173], 1.0 op_sel_hi:[1,0]
	v_pk_add_f32 v[174:175], v[174:175], 1.0 op_sel_hi:[1,0]
	v_pk_add_f32 v[176:177], v[176:177], 1.0 op_sel_hi:[1,0]
	v_pk_add_f32 v[178:179], v[178:179], 1.0 op_sel_hi:[1,0]
	v_rcp_f32_e32 v172, v172
	v_rcp_f32_e32 v173, v173
	v_rcp_f32_e32 v174, v174
	v_rcp_f32_e32 v175, v175
	v_rcp_f32_e32 v176, v176
	v_rcp_f32_e32 v177, v177
	v_rcp_f32_e32 v178, v178
	v_rcp_f32_e32 v179, v179
	s_mov_b64 s[0:1], 0xb0000
	v_lshl_add_u64 v[196:197], v[192:193], 0, s[0:1]
	v_pk_fma_f32 v[172:173], v[172:173], s[20:21], 0.5 op_sel_hi:[1,0,0]
	v_pk_fma_f32 v[174:175], v[174:175], s[20:21], 0.5 op_sel_hi:[1,0,0]
	v_pk_fma_f32 v[176:177], v[176:177], s[20:21], 0.5 op_sel_hi:[1,0,0]
	v_pk_fma_f32 v[178:179], v[178:179], s[20:21], 0.5 op_sel_hi:[1,0,0]
	v_max_f32_e32 v172, 1.0, v172
	v_max_f32_e32 v173, 1.0, v173
	v_max_f32_e32 v174, 1.0, v174
	v_max_f32_e32 v175, 1.0, v175
	v_max_f32_e32 v176, 1.0, v176
	v_max_f32_e32 v177, 1.0, v177
	v_max_f32_e32 v178, 1.0, v178
	v_max_f32_e32 v179, 1.0, v179
	v_cvt_u32_f32_e32 v180, v172
	v_cvt_u32_f32_e32 v181, v176
	v_cvt_u32_f32_sdwa v180, v173 dst_sel:BYTE_1 dst_unused:UNUSED_PRESERVE src0_sel:DWORD
	v_cvt_u32_f32_sdwa v181, v177 dst_sel:BYTE_1 dst_unused:UNUSED_PRESERVE src0_sel:DWORD
	v_cvt_u32_f32_sdwa v180, v174 dst_sel:BYTE_2 dst_unused:UNUSED_PRESERVE src0_sel:DWORD
	v_cvt_u32_f32_sdwa v181, v178 dst_sel:BYTE_2 dst_unused:UNUSED_PRESERVE src0_sel:DWORD
	v_cvt_u32_f32_sdwa v180, v175 dst_sel:BYTE_3 dst_unused:UNUSED_PRESERVE src0_sel:DWORD
	v_cvt_u32_f32_sdwa v181, v179 dst_sel:BYTE_3 dst_unused:UNUSED_PRESERVE src0_sel:DWORD
	global_store_dwordx2 v[196:197], v[180:181], off
	v_pk_mul_f32 v[182:183], v[6:7], s[20:21] op_sel:[0,1] op_sel_hi:[1,1]
	v_pk_mul_f32 v[184:185], v[8:9], s[20:21] op_sel:[0,1] op_sel_hi:[1,1]
	v_pk_mul_f32 v[186:187], v[2:3], s[20:21] op_sel:[0,1] op_sel_hi:[1,1]
	v_pk_mul_f32 v[188:189], v[4:5], s[20:21] op_sel:[0,1] op_sel_hi:[1,1]
	v_exp_f32_e32 v182, v182
	v_exp_f32_e32 v183, v183
	v_exp_f32_e32 v184, v184
	v_exp_f32_e32 v185, v185
	v_exp_f32_e32 v186, v186
	v_exp_f32_e32 v187, v187
	v_exp_f32_e32 v188, v188
	v_exp_f32_e32 v189, v189
	v_pk_add_f32 v[182:183], v[182:183], 1.0 op_sel_hi:[1,0]
	v_pk_add_f32 v[184:185], v[184:185], 1.0 op_sel_hi:[1,0]
	v_pk_add_f32 v[186:187], v[186:187], 1.0 op_sel_hi:[1,0]
	v_pk_add_f32 v[188:189], v[188:189], 1.0 op_sel_hi:[1,0]
	v_rcp_f32_e32 v182, v182
	v_rcp_f32_e32 v183, v183
	v_rcp_f32_e32 v184, v184
	v_rcp_f32_e32 v185, v185
	v_rcp_f32_e32 v186, v186
	v_rcp_f32_e32 v187, v187
	v_rcp_f32_e32 v188, v188
	v_rcp_f32_e32 v189, v189
	s_nop 0
	v_pk_fma_f32 v[182:183], v[182:183], s[20:21], 0.5 op_sel_hi:[1,0,0]
	v_pk_fma_f32 v[184:185], v[184:185], s[20:21], 0.5 op_sel_hi:[1,0,0]
	v_pk_fma_f32 v[186:187], v[186:187], s[20:21], 0.5 op_sel_hi:[1,0,0]
	v_pk_fma_f32 v[188:189], v[188:189], s[20:21], 0.5 op_sel_hi:[1,0,0]
	v_max_f32_e32 v182, 1.0, v182
	v_max_f32_e32 v183, 1.0, v183
	v_max_f32_e32 v184, 1.0, v184
	v_max_f32_e32 v185, 1.0, v185
	v_max_f32_e32 v186, 1.0, v186
	v_max_f32_e32 v187, 1.0, v187
	v_max_f32_e32 v188, 1.0, v188
	v_max_f32_e32 v189, 1.0, v189
	v_cvt_u32_f32_e32 v190, v182
	v_cvt_u32_f32_e32 v191, v186
	v_cvt_u32_f32_sdwa v190, v183 dst_sel:BYTE_1 dst_unused:UNUSED_PRESERVE src0_sel:DWORD
	v_cvt_u32_f32_sdwa v191, v187 dst_sel:BYTE_1 dst_unused:UNUSED_PRESERVE src0_sel:DWORD
	v_cvt_u32_f32_sdwa v190, v184 dst_sel:BYTE_2 dst_unused:UNUSED_PRESERVE src0_sel:DWORD
	v_cvt_u32_f32_sdwa v191, v188 dst_sel:BYTE_2 dst_unused:UNUSED_PRESERVE src0_sel:DWORD
	v_cvt_u32_f32_sdwa v190, v185 dst_sel:BYTE_3 dst_unused:UNUSED_PRESERVE src0_sel:DWORD
	v_cvt_u32_f32_sdwa v191, v189 dst_sel:BYTE_3 dst_unused:UNUSED_PRESERVE src0_sel:DWORD
	global_store_dwordx2 v[196:197], v[190:191], off offset:128
